# K-loop heads aligned to 64 bytes (.p2align 6; padding sits behind the peel's s_branch, never executed); on top of v022
# baseline (speedup 1.0000x reference)
.LBB0_183:
	s_ashr_i32 s13, s12, 31
	s_lshl_b64 s[24:25], s[12:13], 19
	s_add_u32 s24, s80, s24
	s_addc_u32 s25, s81, s25
	s_and_b64 s[30:31], s[4:5], exec
	s_cselect_b32 s13, s25, s45
	s_cselect_b32 s66, s24, s44
	s_ashr_i32 s11, s10, 31
	s_lshl_b64 s[30:31], s[10:11], 19
	s_add_u32 s30, s52, s30
	s_addc_u32 s31, s53, s31
	s_and_b64 s[48:49], s[4:5], exec
	s_cselect_b32 s11, s31, s47
	s_cselect_b32 s67, s30, s46
	s_add_u32 s44, s44, 0x40080
	s_addc_u32 s45, s45, 0
	s_add_u32 s68, s46, 0x100
	s_addc_u32 s69, s47, 0
	s_mov_b32 s70, -2
	ds_read_b128 v[140:143], v147
	ds_read_b128 v[150:153], v147 offset:1024
	ds_read_b128 v[154:157], v147 offset:2048
	ds_read_b128 v[158:161], v147 offset:3072
	ds_read_b128 v[162:165], v148
	ds_read_b128 v[166:169], v148 offset:1024
	ds_read_b128 v[170:173], v148 offset:2048
	ds_read_b128 v[174:177], v148 offset:3072
	s_add_u32 s18, s44, 0xfffc0080
	s_addc_u32 s19, s45, -1
	s_cmp_eq_u32 s70, 12
	s_cselect_b32 s49, s13, s19
	s_cselect_b32 s48, s66, s18
	s_cselect_b32 s47, s11, s69
	s_cselect_b32 s46, s67, s68
	v_lshl_add_u64 v[178:179], s[44:45], 0, v[132:133]
	s_add_i32 m0, s37, 0xc000
	ds_read_b128 v[184:187], v149
	ds_read_b128 v[188:191], v149 offset:1024
	ds_read_b128 v[192:195], v149 offset:2048
	ds_read_b128 v[196:199], v149 offset:3072
	ds_read_b128 v[200:203], v149 offset:4096
	ds_read_b128 v[204:207], v149 offset:5120
	ds_read_b128 v[208:211], v149 offset:6144
	ds_read_b128 v[212:215], v149 offset:7168
	global_load_lds_dwordx4 v[178:179], off
	v_lshl_add_u64 v[178:179], s[44:45], 0, v[134:135]
	s_add_i32 m0, s37, 0xe000
	s_nop 0
	global_load_lds_dwordx4 v[178:179], off
	s_waitcnt vmcnt(8)
	s_waitcnt lgkmcnt(0)
	s_barrier
	s_setprio 1
	s_waitcnt lgkmcnt(0)
	v_mfma_f32_16x16x32_bf16 v[124:127], v[140:143], v[184:187], 0
	v_mfma_f32_16x16x32_bf16 v[124:127], v[150:153], v[188:191], v[124:127]
	v_mfma_f32_16x16x32_bf16 v[120:123], v[154:157], v[184:187], 0
	v_mfma_f32_16x16x32_bf16 v[120:123], v[158:161], v[188:191], v[120:123]
	v_mfma_f32_16x16x32_bf16 v[108:111], v[140:143], v[192:195], 0
	v_mfma_f32_16x16x32_bf16 v[108:111], v[150:153], v[196:199], v[108:111]
	v_mfma_f32_16x16x32_bf16 v[104:107], v[154:157], v[192:195], 0
	v_mfma_f32_16x16x32_bf16 v[104:107], v[158:161], v[196:199], v[104:107]
	v_mfma_f32_16x16x32_bf16 v[92:95], v[140:143], v[200:203], 0
	v_mfma_f32_16x16x32_bf16 v[92:95], v[150:153], v[204:207], v[92:95]
	v_mfma_f32_16x16x32_bf16 v[88:91], v[154:157], v[200:203], 0
	v_mfma_f32_16x16x32_bf16 v[88:91], v[158:161], v[204:207], v[88:91]
	v_mfma_f32_16x16x32_bf16 v[76:79], v[140:143], v[208:211], 0
	v_mfma_f32_16x16x32_bf16 v[76:79], v[150:153], v[212:215], v[76:79]
	v_mfma_f32_16x16x32_bf16 v[72:75], v[154:157], v[208:211], 0
	v_mfma_f32_16x16x32_bf16 v[72:75], v[158:161], v[212:215], v[72:75]
	v_mfma_f32_16x16x32_bf16 v[116:119], v[162:165], v[184:187], 0
	v_mfma_f32_16x16x32_bf16 v[116:119], v[166:169], v[188:191], v[116:119]
	v_mfma_f32_16x16x32_bf16 v[112:115], v[170:173], v[184:187], 0
	v_mfma_f32_16x16x32_bf16 v[112:115], v[174:177], v[188:191], v[112:115]
	v_mfma_f32_16x16x32_bf16 v[100:103], v[162:165], v[192:195], 0
	v_mfma_f32_16x16x32_bf16 v[100:103], v[166:169], v[196:199], v[100:103]
	v_mfma_f32_16x16x32_bf16 v[96:99], v[170:173], v[192:195], 0
	v_mfma_f32_16x16x32_bf16 v[96:99], v[174:177], v[196:199], v[96:99]
	v_mfma_f32_16x16x32_bf16 v[84:87], v[162:165], v[200:203], 0
	v_mfma_f32_16x16x32_bf16 v[84:87], v[166:169], v[204:207], v[84:87]
	v_mfma_f32_16x16x32_bf16 v[80:83], v[170:173], v[200:203], 0
	v_mfma_f32_16x16x32_bf16 v[80:83], v[174:177], v[204:207], v[80:83]
	v_mfma_f32_16x16x32_bf16 v[68:71], v[162:165], v[208:211], 0
	v_mfma_f32_16x16x32_bf16 v[68:71], v[166:169], v[212:215], v[68:71]
	v_mfma_f32_16x16x32_bf16 v[64:67], v[170:173], v[208:211], 0
	v_mfma_f32_16x16x32_bf16 v[64:67], v[174:177], v[212:215], v[64:67]
	s_setprio 0
	s_barrier
	s_add_i32 s18, s62, s54
	v_lshl_add_u64 v[178:179], s[46:47], 0, v[130:131]
	s_mov_b32 m0, s18
	ds_read_b128 v[184:187], v149 offset:16384
	ds_read_b128 v[188:191], v149 offset:17408
	ds_read_b128 v[192:195], v149 offset:18432
	ds_read_b128 v[196:199], v149 offset:19456
	ds_read_b128 v[200:203], v149 offset:20480
	ds_read_b128 v[204:207], v149 offset:21504
	ds_read_b128 v[208:211], v149 offset:22528
	ds_read_b128 v[212:215], v149 offset:23552
	global_load_lds_dwordx4 v[178:179], off
	s_add_i32 m0, s18, 0x2000
	s_add_u32 s72, s46, 0x40000
	v_lshl_add_u64 v[216:217], s[46:47], 0, v[128:129]
	s_addc_u32 s73, s47, 0
	s_add_i32 s18, s63, s54
	global_load_lds_dwordx4 v[216:217], off
	v_lshl_add_u64 v[218:219], s[72:73], 0, v[130:131]
	s_mov_b32 m0, s18
	v_lshl_add_u64 v[220:221], s[48:49], 0, v[128:129]
	global_load_lds_dwordx4 v[218:219], off
	v_lshl_add_u64 v[218:219], s[72:73], 0, v[128:129]
	s_add_i32 m0, s18, 0x2000
	s_nop 0
	global_load_lds_dwordx4 v[218:219], off
	v_lshl_add_u64 v[218:219], s[48:49], 0, v[130:131]
	s_mov_b32 m0, s37
	s_nop 0
	global_load_lds_dwordx4 v[218:219], off
	s_mov_b32 m0, s56
	s_nop 0
	global_load_lds_dwordx4 v[220:221], off
	s_waitcnt vmcnt(8)
	s_waitcnt lgkmcnt(0)
	s_barrier
	s_setprio 1
	s_waitcnt lgkmcnt(0)
	v_mfma_f32_16x16x32_bf16 v[60:63], v[140:143], v[184:187], 0
	v_mfma_f32_16x16x32_bf16 v[60:63], v[150:153], v[188:191], v[60:63]
	v_mfma_f32_16x16x32_bf16 v[56:59], v[154:157], v[184:187], 0
	v_mfma_f32_16x16x32_bf16 v[56:59], v[158:161], v[188:191], v[56:59]
	v_mfma_f32_16x16x32_bf16 v[44:47], v[140:143], v[192:195], 0
	v_mfma_f32_16x16x32_bf16 v[44:47], v[150:153], v[196:199], v[44:47]
	v_mfma_f32_16x16x32_bf16 v[40:43], v[154:157], v[192:195], 0
	v_mfma_f32_16x16x32_bf16 v[40:43], v[158:161], v[196:199], v[40:43]
	v_mfma_f32_16x16x32_bf16 v[28:31], v[140:143], v[200:203], 0
	v_mfma_f32_16x16x32_bf16 v[28:31], v[150:153], v[204:207], v[28:31]
	v_mfma_f32_16x16x32_bf16 v[24:27], v[154:157], v[200:203], 0
	v_mfma_f32_16x16x32_bf16 v[24:27], v[158:161], v[204:207], v[24:27]
	v_mfma_f32_16x16x32_bf16 v[12:15], v[140:143], v[208:211], 0
	v_mfma_f32_16x16x32_bf16 v[12:15], v[150:153], v[212:215], v[12:15]
	v_mfma_f32_16x16x32_bf16 v[8:11], v[154:157], v[208:211], 0
	v_mfma_f32_16x16x32_bf16 v[8:11], v[158:161], v[212:215], v[8:11]
	v_mfma_f32_16x16x32_bf16 v[52:55], v[162:165], v[184:187], 0
	v_mfma_f32_16x16x32_bf16 v[52:55], v[166:169], v[188:191], v[52:55]
	v_mfma_f32_16x16x32_bf16 v[48:51], v[170:173], v[184:187], 0
	v_mfma_f32_16x16x32_bf16 v[48:51], v[174:177], v[188:191], v[48:51]
	v_mfma_f32_16x16x32_bf16 v[36:39], v[162:165], v[192:195], 0
	v_mfma_f32_16x16x32_bf16 v[36:39], v[166:169], v[196:199], v[36:39]
	v_mfma_f32_16x16x32_bf16 v[32:35], v[170:173], v[192:195], 0
	v_mfma_f32_16x16x32_bf16 v[32:35], v[174:177], v[196:199], v[32:35]
	v_mfma_f32_16x16x32_bf16 v[20:23], v[162:165], v[200:203], 0
	v_mfma_f32_16x16x32_bf16 v[20:23], v[166:169], v[204:207], v[20:23]
	v_mfma_f32_16x16x32_bf16 v[16:19], v[170:173], v[200:203], 0
	v_mfma_f32_16x16x32_bf16 v[16:19], v[174:177], v[204:207], v[16:19]
	v_mfma_f32_16x16x32_bf16 v[4:7], v[162:165], v[208:211], 0
	v_mfma_f32_16x16x32_bf16 v[4:7], v[166:169], v[212:215], v[4:7]
	v_mfma_f32_16x16x32_bf16 v[0:3], v[170:173], v[208:211], 0
	v_mfma_f32_16x16x32_bf16 v[0:3], v[174:177], v[212:215], v[0:3]
	s_setprio 0
	s_barrier
	s_branch .Lmid_gemm0
	.p2align	6

.LBB0_263:
	s_add_u32 s84, s54, 0x100
	s_addc_u32 s85, s55, 0
	s_mov_b32 s86, -2
	ds_read_b128 v[152:155], v149
	ds_read_b128 v[156:159], v149 offset:1024
	ds_read_b128 v[160:163], v149 offset:2048
	ds_read_b128 v[164:167], v149 offset:3072
	ds_read_b128 v[168:171], v150
	ds_read_b128 v[172:175], v150 offset:1024
	ds_read_b128 v[176:179], v150 offset:2048
	ds_read_b128 v[184:187], v150 offset:3072
	s_add_u32 s54, s52, 0x100
	s_addc_u32 s55, s53, 0
	s_cmp_eq_u32 s86, 40
	s_cselect_b32 s59, s7, s55
	s_cselect_b32 s58, s6, s54
	s_cselect_b32 s57, s49, s85
	s_cselect_b32 s56, s48, s84
	v_lshl_add_u64 v[144:145], s[52:53], 0, v[136:137]
	s_add_i32 m0, s63, 0xc000
	ds_read_b128 v[188:191], v151
	ds_read_b128 v[192:195], v151 offset:1024
	ds_read_b128 v[196:199], v151 offset:2048
	ds_read_b128 v[200:203], v151 offset:3072
	ds_read_b128 v[204:207], v151 offset:4096
	ds_read_b128 v[208:211], v151 offset:5120
	ds_read_b128 v[212:215], v151 offset:6144
	ds_read_b128 v[216:219], v151 offset:7168
	global_load_lds_dwordx4 v[144:145], off
	v_lshl_add_u64 v[144:145], s[52:53], 0, v[138:139]
	s_add_i32 m0, s63, 0xe000
	s_nop 0
	global_load_lds_dwordx4 v[144:145], off
	s_waitcnt vmcnt(8)
	s_waitcnt lgkmcnt(0)
	s_barrier
	s_setprio 1
	s_waitcnt lgkmcnt(0)
	v_mfma_f32_16x16x32_bf16 v[124:127], v[152:155], v[188:191], 0
	v_mfma_f32_16x16x32_bf16 v[124:127], v[156:159], v[192:195], v[124:127]
	v_mfma_f32_16x16x32_bf16 v[120:123], v[160:163], v[188:191], 0
	v_mfma_f32_16x16x32_bf16 v[120:123], v[164:167], v[192:195], v[120:123]
	v_mfma_f32_16x16x32_bf16 v[116:119], v[152:155], v[196:199], 0
	v_mfma_f32_16x16x32_bf16 v[116:119], v[156:159], v[200:203], v[116:119]
	v_mfma_f32_16x16x32_bf16 v[108:111], v[160:163], v[196:199], 0
	v_mfma_f32_16x16x32_bf16 v[108:111], v[164:167], v[200:203], v[108:111]
	v_mfma_f32_16x16x32_bf16 v[100:103], v[152:155], v[204:207], 0
	v_mfma_f32_16x16x32_bf16 v[100:103], v[156:159], v[208:211], v[100:103]
	v_mfma_f32_16x16x32_bf16 v[92:95], v[160:163], v[204:207], 0
	v_mfma_f32_16x16x32_bf16 v[92:95], v[164:167], v[208:211], v[92:95]
	v_mfma_f32_16x16x32_bf16 v[84:87], v[152:155], v[212:215], 0
	v_mfma_f32_16x16x32_bf16 v[84:87], v[156:159], v[216:219], v[84:87]
	v_mfma_f32_16x16x32_bf16 v[76:79], v[160:163], v[212:215], 0
	v_mfma_f32_16x16x32_bf16 v[76:79], v[164:167], v[216:219], v[76:79]
	v_mfma_f32_16x16x32_bf16 v[112:115], v[168:171], v[188:191], 0
	v_mfma_f32_16x16x32_bf16 v[112:115], v[172:175], v[192:195], v[112:115]
	v_mfma_f32_16x16x32_bf16 v[104:107], v[176:179], v[188:191], 0
	v_mfma_f32_16x16x32_bf16 v[104:107], v[184:187], v[192:195], v[104:107]
	v_mfma_f32_16x16x32_bf16 v[96:99], v[168:171], v[196:199], 0
	v_mfma_f32_16x16x32_bf16 v[96:99], v[172:175], v[200:203], v[96:99]
	v_mfma_f32_16x16x32_bf16 v[88:91], v[176:179], v[196:199], 0
	v_mfma_f32_16x16x32_bf16 v[88:91], v[184:187], v[200:203], v[88:91]
	v_mfma_f32_16x16x32_bf16 v[80:83], v[168:171], v[204:207], 0
	v_mfma_f32_16x16x32_bf16 v[80:83], v[172:175], v[208:211], v[80:83]
	v_mfma_f32_16x16x32_bf16 v[72:75], v[176:179], v[204:207], 0
	v_mfma_f32_16x16x32_bf16 v[72:75], v[184:187], v[208:211], v[72:75]
	v_mfma_f32_16x16x32_bf16 v[68:71], v[168:171], v[212:215], 0
	v_mfma_f32_16x16x32_bf16 v[68:71], v[172:175], v[216:219], v[68:71]
	v_mfma_f32_16x16x32_bf16 v[64:67], v[176:179], v[212:215], 0
	v_mfma_f32_16x16x32_bf16 v[64:67], v[184:187], v[216:219], v[64:67]
	s_setprio 0
	s_barrier
	s_add_i32 s18, s70, s62
	v_lshl_add_u64 v[144:145], s[56:57], 0, v[130:131]
	s_mov_b32 m0, s18
	ds_read_b128 v[188:191], v151 offset:16384
	ds_read_b128 v[192:195], v151 offset:17408
	ds_read_b128 v[196:199], v151 offset:18432
	ds_read_b128 v[200:203], v151 offset:19456
	ds_read_b128 v[204:207], v151 offset:20480
	ds_read_b128 v[208:211], v151 offset:21504
	ds_read_b128 v[212:215], v151 offset:22528
	ds_read_b128 v[216:219], v151 offset:23552
	global_load_lds_dwordx4 v[144:145], off
	s_add_i32 m0, s18, 0x2000
	s_add_u32 s52, s56, 0xb0000
	v_lshl_add_u64 v[220:221], s[56:57], 0, v[134:135]
	s_addc_u32 s53, s57, 0
	s_add_i32 s18, s71, s62
	global_load_lds_dwordx4 v[220:221], off
	v_lshl_add_u64 v[222:223], s[52:53], 0, v[130:131]
	s_mov_b32 m0, s18
	v_lshl_add_u64 v[224:225], s[58:59], 0, v[132:133]
	global_load_lds_dwordx4 v[222:223], off
	v_lshl_add_u64 v[222:223], s[52:53], 0, v[134:135]
	s_add_i32 m0, s18, 0x2000
	s_nop 0
	global_load_lds_dwordx4 v[222:223], off
	v_lshl_add_u64 v[222:223], s[58:59], 0, v[128:129]
	s_mov_b32 m0, s63
	s_nop 0
	global_load_lds_dwordx4 v[222:223], off
	s_mov_b32 m0, s64
	s_nop 0
	global_load_lds_dwordx4 v[224:225], off
	s_waitcnt vmcnt(8)
	s_waitcnt lgkmcnt(0)
	s_barrier
	s_setprio 1
	s_waitcnt lgkmcnt(0)
	v_mfma_f32_16x16x32_bf16 v[60:63], v[152:155], v[188:191], 0
	v_mfma_f32_16x16x32_bf16 v[60:63], v[156:159], v[192:195], v[60:63]
	v_mfma_f32_16x16x32_bf16 v[56:59], v[160:163], v[188:191], 0
	v_mfma_f32_16x16x32_bf16 v[56:59], v[164:167], v[192:195], v[56:59]
	v_mfma_f32_16x16x32_bf16 v[52:55], v[152:155], v[196:199], 0
	v_mfma_f32_16x16x32_bf16 v[52:55], v[156:159], v[200:203], v[52:55]
	v_mfma_f32_16x16x32_bf16 v[44:47], v[160:163], v[196:199], 0
	v_mfma_f32_16x16x32_bf16 v[44:47], v[164:167], v[200:203], v[44:47]
	v_mfma_f32_16x16x32_bf16 v[36:39], v[152:155], v[204:207], 0
	v_mfma_f32_16x16x32_bf16 v[36:39], v[156:159], v[208:211], v[36:39]
	v_mfma_f32_16x16x32_bf16 v[28:31], v[160:163], v[204:207], 0
	v_mfma_f32_16x16x32_bf16 v[28:31], v[164:167], v[208:211], v[28:31]
	v_mfma_f32_16x16x32_bf16 v[20:23], v[152:155], v[212:215], 0
	v_mfma_f32_16x16x32_bf16 v[20:23], v[156:159], v[216:219], v[20:23]
	v_mfma_f32_16x16x32_bf16 v[12:15], v[160:163], v[212:215], 0
	v_mfma_f32_16x16x32_bf16 v[12:15], v[164:167], v[216:219], v[12:15]
	v_mfma_f32_16x16x32_bf16 v[48:51], v[168:171], v[188:191], 0
	v_mfma_f32_16x16x32_bf16 v[48:51], v[172:175], v[192:195], v[48:51]
	v_mfma_f32_16x16x32_bf16 v[40:43], v[176:179], v[188:191], 0
	v_mfma_f32_16x16x32_bf16 v[40:43], v[184:187], v[192:195], v[40:43]
	v_mfma_f32_16x16x32_bf16 v[32:35], v[168:171], v[196:199], 0
	v_mfma_f32_16x16x32_bf16 v[32:35], v[172:175], v[200:203], v[32:35]
	v_mfma_f32_16x16x32_bf16 v[24:27], v[176:179], v[196:199], 0
	v_mfma_f32_16x16x32_bf16 v[24:27], v[184:187], v[200:203], v[24:27]
	v_mfma_f32_16x16x32_bf16 v[16:19], v[168:171], v[204:207], 0
	v_mfma_f32_16x16x32_bf16 v[16:19], v[172:175], v[208:211], v[16:19]
	v_mfma_f32_16x16x32_bf16 v[8:11], v[176:179], v[204:207], 0
	v_mfma_f32_16x16x32_bf16 v[8:11], v[184:187], v[208:211], v[8:11]
	v_mfma_f32_16x16x32_bf16 v[4:7], v[168:171], v[212:215], 0
	v_mfma_f32_16x16x32_bf16 v[4:7], v[172:175], v[216:219], v[4:7]
	v_mfma_f32_16x16x32_bf16 v[0:3], v[176:179], v[212:215], 0
	v_mfma_f32_16x16x32_bf16 v[0:3], v[184:187], v[216:219], v[0:3]
	s_setprio 0
	s_barrier
	s_branch .Lmid_gemm1
	.p2align	6

.LBB0_386:
	s_ashr_i32 s49, s48, 31
	s_lshl_b64 s[52:53], s[48:49], 19
	s_add_u32 s52, s80, s52
	s_addc_u32 s53, s81, s53
	s_and_b64 s[54:55], s[4:5], exec
	s_cselect_b32 s49, s53, s59
	s_cselect_b32 s82, s52, s58
	s_ashr_i32 s47, s46, 31
	s_lshl_b64 s[54:55], s[46:47], 19
	s_add_u32 s54, s64, s54
	s_addc_u32 s55, s65, s55
	s_and_b64 s[62:63], s[4:5], exec
	s_cselect_b32 s47, s55, s61
	s_cselect_b32 s83, s54, s60
	s_add_u32 s58, s58, 0x40080
	s_addc_u32 s59, s59, 0
	s_add_u32 s84, s60, 0x100
	s_addc_u32 s85, s61, 0
	s_mov_b32 s86, -2
	ds_read_b128 v[152:155], v148
	ds_read_b128 v[156:159], v148 offset:1024
	ds_read_b128 v[160:163], v148 offset:2048
	ds_read_b128 v[164:167], v148 offset:3072
	ds_read_b128 v[168:171], v149
	ds_read_b128 v[172:175], v149 offset:1024
	ds_read_b128 v[176:179], v149 offset:2048
	ds_read_b128 v[184:187], v149 offset:3072
	s_add_u32 s18, s58, 0xfffc0080
	s_addc_u32 s19, s59, -1
	s_cmp_eq_u32 s86, 12
	s_cselect_b32 s63, s49, s19
	s_cselect_b32 s62, s82, s18
	s_cselect_b32 s61, s47, s85
	s_cselect_b32 s60, s83, s84
	v_lshl_add_u64 v[220:221], s[58:59], 0, v[138:139]
	s_add_i32 m0, s68, 0xc000
	ds_read_b128 v[188:191], v150
	ds_read_b128 v[192:195], v150 offset:1024
	ds_read_b128 v[196:199], v150 offset:2048
	ds_read_b128 v[200:203], v150 offset:3072
	ds_read_b128 v[204:207], v150 offset:4096
	ds_read_b128 v[208:211], v150 offset:5120
	ds_read_b128 v[212:215], v150 offset:6144
	ds_read_b128 v[216:219], v150 offset:7168
	global_load_lds_dwordx4 v[220:221], off
	v_lshl_add_u64 v[220:221], s[58:59], 0, v[140:141]
	s_add_i32 m0, s68, 0xe000
	s_nop 0
	global_load_lds_dwordx4 v[220:221], off
	s_waitcnt vmcnt(8)
	s_waitcnt lgkmcnt(0)
	s_barrier
	s_setprio 1
	s_waitcnt lgkmcnt(0)
	v_mfma_f32_16x16x32_bf16 v[124:127], v[152:155], v[188:191], 0
	v_mfma_f32_16x16x32_bf16 v[124:127], v[156:159], v[192:195], v[124:127]
	v_mfma_f32_16x16x32_bf16 v[120:123], v[160:163], v[188:191], 0
	v_mfma_f32_16x16x32_bf16 v[120:123], v[164:167], v[192:195], v[120:123]
	v_mfma_f32_16x16x32_bf16 v[116:119], v[152:155], v[196:199], 0
	v_mfma_f32_16x16x32_bf16 v[116:119], v[156:159], v[200:203], v[116:119]
	v_mfma_f32_16x16x32_bf16 v[112:115], v[160:163], v[196:199], 0
	v_mfma_f32_16x16x32_bf16 v[112:115], v[164:167], v[200:203], v[112:115]
	v_mfma_f32_16x16x32_bf16 v[108:111], v[152:155], v[204:207], 0
	v_mfma_f32_16x16x32_bf16 v[108:111], v[156:159], v[208:211], v[108:111]
	v_mfma_f32_16x16x32_bf16 v[104:107], v[160:163], v[204:207], 0
	v_mfma_f32_16x16x32_bf16 v[104:107], v[164:167], v[208:211], v[104:107]
	v_mfma_f32_16x16x32_bf16 v[100:103], v[152:155], v[212:215], 0
	v_mfma_f32_16x16x32_bf16 v[100:103], v[156:159], v[216:219], v[100:103]
	v_mfma_f32_16x16x32_bf16 v[96:99], v[160:163], v[212:215], 0
	v_mfma_f32_16x16x32_bf16 v[96:99], v[164:167], v[216:219], v[96:99]
	v_mfma_f32_16x16x32_bf16 v[68:71], v[168:171], v[188:191], 0
	v_mfma_f32_16x16x32_bf16 v[68:71], v[172:175], v[192:195], v[68:71]
	v_mfma_f32_16x16x32_bf16 v[64:67], v[176:179], v[188:191], 0
	v_mfma_f32_16x16x32_bf16 v[64:67], v[184:187], v[192:195], v[64:67]
	v_mfma_f32_16x16x32_bf16 v[52:55], v[168:171], v[196:199], 0
	v_mfma_f32_16x16x32_bf16 v[52:55], v[172:175], v[200:203], v[52:55]
	v_mfma_f32_16x16x32_bf16 v[48:51], v[176:179], v[196:199], 0
	v_mfma_f32_16x16x32_bf16 v[48:51], v[184:187], v[200:203], v[48:51]
	v_mfma_f32_16x16x32_bf16 v[44:47], v[168:171], v[204:207], 0
	v_mfma_f32_16x16x32_bf16 v[44:47], v[172:175], v[208:211], v[44:47]
	v_mfma_f32_16x16x32_bf16 v[40:43], v[176:179], v[204:207], 0
	v_mfma_f32_16x16x32_bf16 v[40:43], v[184:187], v[208:211], v[40:43]
	v_mfma_f32_16x16x32_bf16 v[36:39], v[168:171], v[212:215], 0
	v_mfma_f32_16x16x32_bf16 v[36:39], v[172:175], v[216:219], v[36:39]
	v_mfma_f32_16x16x32_bf16 v[32:35], v[176:179], v[212:215], 0
	v_mfma_f32_16x16x32_bf16 v[32:35], v[184:187], v[216:219], v[32:35]
	s_setprio 0
	s_barrier
	s_add_i32 s18, s76, s66
	v_lshl_add_u64 v[220:221], s[60:61], 0, v[132:133]
	s_mov_b32 m0, s18
	ds_read_b128 v[188:191], v150 offset:16384
	ds_read_b128 v[192:195], v150 offset:17408
	ds_read_b128 v[196:199], v150 offset:18432
	ds_read_b128 v[200:203], v150 offset:19456
	ds_read_b128 v[204:207], v150 offset:20480
	ds_read_b128 v[208:211], v150 offset:21504
	ds_read_b128 v[212:215], v150 offset:22528
	ds_read_b128 v[216:219], v150 offset:23552
	global_load_lds_dwordx4 v[220:221], off
	s_add_i32 m0, s18, 0x2000
	s_add_u32 s88, s60, 0x40000
	v_lshl_add_u64 v[222:223], s[60:61], 0, v[128:129]
	s_addc_u32 s89, s61, 0
	s_add_i32 s18, s77, s66
	global_load_lds_dwordx4 v[222:223], off
	v_lshl_add_u64 v[224:225], s[88:89], 0, v[132:133]
	s_mov_b32 m0, s18
	v_lshl_add_u64 v[226:227], s[62:63], 0, v[130:131]
	global_load_lds_dwordx4 v[224:225], off
	v_lshl_add_u64 v[224:225], s[88:89], 0, v[128:129]
	s_add_i32 m0, s18, 0x2000
	s_nop 0
	global_load_lds_dwordx4 v[224:225], off
	v_lshl_add_u64 v[224:225], s[62:63], 0, v[134:135]
	s_mov_b32 m0, s68
	s_nop 0
	global_load_lds_dwordx4 v[224:225], off
	s_mov_b32 m0, s69
	s_nop 0
	global_load_lds_dwordx4 v[226:227], off
	s_waitcnt vmcnt(8)
	s_waitcnt lgkmcnt(0)
	s_barrier
	s_setprio 1
	s_waitcnt lgkmcnt(0)
	v_mfma_f32_16x16x32_bf16 v[92:95], v[152:155], v[188:191], 0
	v_mfma_f32_16x16x32_bf16 v[92:95], v[156:159], v[192:195], v[92:95]
	v_mfma_f32_16x16x32_bf16 v[88:91], v[160:163], v[188:191], 0
	v_mfma_f32_16x16x32_bf16 v[88:91], v[164:167], v[192:195], v[88:91]
	v_mfma_f32_16x16x32_bf16 v[84:87], v[152:155], v[196:199], 0
	v_mfma_f32_16x16x32_bf16 v[84:87], v[156:159], v[200:203], v[84:87]
	v_mfma_f32_16x16x32_bf16 v[80:83], v[160:163], v[196:199], 0
	v_mfma_f32_16x16x32_bf16 v[80:83], v[164:167], v[200:203], v[80:83]
	v_mfma_f32_16x16x32_bf16 v[76:79], v[152:155], v[204:207], 0
	v_mfma_f32_16x16x32_bf16 v[76:79], v[156:159], v[208:211], v[76:79]
	v_mfma_f32_16x16x32_bf16 v[72:75], v[160:163], v[204:207], 0
	v_mfma_f32_16x16x32_bf16 v[72:75], v[164:167], v[208:211], v[72:75]
	v_mfma_f32_16x16x32_bf16 v[60:63], v[152:155], v[212:215], 0
	v_mfma_f32_16x16x32_bf16 v[60:63], v[156:159], v[216:219], v[60:63]
	v_mfma_f32_16x16x32_bf16 v[56:59], v[160:163], v[212:215], 0
	v_mfma_f32_16x16x32_bf16 v[56:59], v[164:167], v[216:219], v[56:59]
	v_mfma_f32_16x16x32_bf16 v[28:31], v[168:171], v[188:191], 0
	v_mfma_f32_16x16x32_bf16 v[28:31], v[172:175], v[192:195], v[28:31]
	v_mfma_f32_16x16x32_bf16 v[24:27], v[176:179], v[188:191], 0
	v_mfma_f32_16x16x32_bf16 v[24:27], v[184:187], v[192:195], v[24:27]
	v_mfma_f32_16x16x32_bf16 v[20:23], v[168:171], v[196:199], 0
	v_mfma_f32_16x16x32_bf16 v[20:23], v[172:175], v[200:203], v[20:23]
	v_mfma_f32_16x16x32_bf16 v[16:19], v[176:179], v[196:199], 0
	v_mfma_f32_16x16x32_bf16 v[16:19], v[184:187], v[200:203], v[16:19]
	v_mfma_f32_16x16x32_bf16 v[12:15], v[168:171], v[204:207], 0
	v_mfma_f32_16x16x32_bf16 v[12:15], v[172:175], v[208:211], v[12:15]
	v_mfma_f32_16x16x32_bf16 v[8:11], v[176:179], v[204:207], 0
	v_mfma_f32_16x16x32_bf16 v[8:11], v[184:187], v[208:211], v[8:11]
	v_mfma_f32_16x16x32_bf16 v[4:7], v[168:171], v[212:215], 0
	v_mfma_f32_16x16x32_bf16 v[4:7], v[172:175], v[216:219], v[4:7]
	v_mfma_f32_16x16x32_bf16 v[0:3], v[176:179], v[212:215], 0
	v_mfma_f32_16x16x32_bf16 v[0:3], v[184:187], v[216:219], v[0:3]
	s_setprio 0
	s_barrier
	s_branch .Lmid_gemm2
	.p2align	6

.LBB0_600:
	s_ashr_i32 s49, s48, 31
	s_lshl_b64 s[18:19], s[48:49], 19
	s_add_u32 s52, s38, s18
	s_addc_u32 s53, s39, s19
	s_and_b64 s[18:19], s[4:5], exec
	s_cselect_b32 s49, s53, s59
	s_cselect_b32 s84, s52, s58
	s_ashr_i32 s47, s46, 31
	s_lshl_b64 s[18:19], s[46:47], 19
	s_add_u32 s54, s64, s18
	s_addc_u32 s55, s65, s19
	s_and_b64 s[18:19], s[4:5], exec
	s_cselect_b32 s47, s55, s61
	s_cselect_b32 s85, s54, s60
	s_add_u32 s58, s58, 0x40080
	s_addc_u32 s59, s59, 0
	s_add_u32 s86, s60, 0x100
	s_addc_u32 s87, s61, 0
	s_mov_b32 s88, -2
	ds_read_b128 v[152:155], v149
	ds_read_b128 v[156:159], v149 offset:1024
	ds_read_b128 v[160:163], v149 offset:2048
	ds_read_b128 v[164:167], v149 offset:3072
	ds_read_b128 v[168:171], v150
	ds_read_b128 v[172:175], v150 offset:1024
	ds_read_b128 v[176:179], v150 offset:2048
	ds_read_b128 v[184:187], v150 offset:3072
	s_add_u32 s18, s58, 0xfffc0080
	s_addc_u32 s19, s59, -1
	s_cmp_eq_u32 s88, 12
	s_cselect_b32 s63, s49, s19
	s_cselect_b32 s62, s84, s18
	s_cselect_b32 s61, s47, s87
	s_cselect_b32 s60, s85, s86
	v_lshl_add_u64 v[144:145], s[58:59], 0, v[136:137]
	s_add_i32 m0, s57, 0xc000
	ds_read_b128 v[188:191], v151
	ds_read_b128 v[192:195], v151 offset:1024
	ds_read_b128 v[196:199], v151 offset:2048
	ds_read_b128 v[200:203], v151 offset:3072
	ds_read_b128 v[204:207], v151 offset:4096
	ds_read_b128 v[208:211], v151 offset:5120
	ds_read_b128 v[212:215], v151 offset:6144
	ds_read_b128 v[216:219], v151 offset:7168
	global_load_lds_dwordx4 v[144:145], off
	v_lshl_add_u64 v[144:145], s[58:59], 0, v[138:139]
	s_add_i32 m0, s57, 0xe000
	s_nop 0
	global_load_lds_dwordx4 v[144:145], off
	s_waitcnt vmcnt(8)
	s_waitcnt lgkmcnt(0)
	s_barrier
	s_setprio 1
	s_waitcnt lgkmcnt(0)
	v_mfma_f32_16x16x32_bf16 v[124:127], v[152:155], v[188:191], 0
	v_mfma_f32_16x16x32_bf16 v[124:127], v[156:159], v[192:195], v[124:127]
	v_mfma_f32_16x16x32_bf16 v[120:123], v[160:163], v[188:191], 0
	v_mfma_f32_16x16x32_bf16 v[120:123], v[164:167], v[192:195], v[120:123]
	v_mfma_f32_16x16x32_bf16 v[116:119], v[152:155], v[196:199], 0
	v_mfma_f32_16x16x32_bf16 v[116:119], v[156:159], v[200:203], v[116:119]
	v_mfma_f32_16x16x32_bf16 v[108:111], v[160:163], v[196:199], 0
	v_mfma_f32_16x16x32_bf16 v[108:111], v[164:167], v[200:203], v[108:111]
	v_mfma_f32_16x16x32_bf16 v[100:103], v[152:155], v[204:207], 0
	v_mfma_f32_16x16x32_bf16 v[100:103], v[156:159], v[208:211], v[100:103]
	v_mfma_f32_16x16x32_bf16 v[92:95], v[160:163], v[204:207], 0
	v_mfma_f32_16x16x32_bf16 v[92:95], v[164:167], v[208:211], v[92:95]
	v_mfma_f32_16x16x32_bf16 v[84:87], v[152:155], v[212:215], 0
	v_mfma_f32_16x16x32_bf16 v[84:87], v[156:159], v[216:219], v[84:87]
	v_mfma_f32_16x16x32_bf16 v[76:79], v[160:163], v[212:215], 0
	v_mfma_f32_16x16x32_bf16 v[76:79], v[164:167], v[216:219], v[76:79]
	v_mfma_f32_16x16x32_bf16 v[112:115], v[168:171], v[188:191], 0
	v_mfma_f32_16x16x32_bf16 v[112:115], v[172:175], v[192:195], v[112:115]
	v_mfma_f32_16x16x32_bf16 v[104:107], v[176:179], v[188:191], 0
	v_mfma_f32_16x16x32_bf16 v[104:107], v[184:187], v[192:195], v[104:107]
	v_mfma_f32_16x16x32_bf16 v[96:99], v[168:171], v[196:199], 0
	v_mfma_f32_16x16x32_bf16 v[96:99], v[172:175], v[200:203], v[96:99]
	v_mfma_f32_16x16x32_bf16 v[88:91], v[176:179], v[196:199], 0
	v_mfma_f32_16x16x32_bf16 v[88:91], v[184:187], v[200:203], v[88:91]
	v_mfma_f32_16x16x32_bf16 v[80:83], v[168:171], v[204:207], 0
	v_mfma_f32_16x16x32_bf16 v[80:83], v[172:175], v[208:211], v[80:83]
	v_mfma_f32_16x16x32_bf16 v[72:75], v[176:179], v[204:207], 0
	v_mfma_f32_16x16x32_bf16 v[72:75], v[184:187], v[208:211], v[72:75]
	v_mfma_f32_16x16x32_bf16 v[68:71], v[168:171], v[212:215], 0
	v_mfma_f32_16x16x32_bf16 v[68:71], v[172:175], v[216:219], v[68:71]
	v_mfma_f32_16x16x32_bf16 v[64:67], v[176:179], v[212:215], 0
	v_mfma_f32_16x16x32_bf16 v[64:67], v[184:187], v[216:219], v[64:67]
	s_setprio 0
	s_barrier
	s_add_i32 s18, s73, s66
	v_lshl_add_u64 v[144:145], s[60:61], 0, v[130:131]
	s_mov_b32 m0, s18
	ds_read_b128 v[188:191], v151 offset:16384
	ds_read_b128 v[192:195], v151 offset:17408
	ds_read_b128 v[196:199], v151 offset:18432
	ds_read_b128 v[200:203], v151 offset:19456
	ds_read_b128 v[204:207], v151 offset:20480
	ds_read_b128 v[208:211], v151 offset:21504
	ds_read_b128 v[212:215], v151 offset:22528
	ds_read_b128 v[216:219], v151 offset:23552
	global_load_lds_dwordx4 v[144:145], off
	s_add_i32 m0, s18, 0x2000
	s_add_u32 s18, s60, 0x40000
	v_lshl_add_u64 v[220:221], s[60:61], 0, v[134:135]
	s_addc_u32 s19, s61, 0
	s_add_i32 s79, s74, s66
	global_load_lds_dwordx4 v[220:221], off
	v_lshl_add_u64 v[222:223], s[18:19], 0, v[130:131]
	s_mov_b32 m0, s79
	v_lshl_add_u64 v[224:225], s[62:63], 0, v[132:133]
	global_load_lds_dwordx4 v[222:223], off
	v_lshl_add_u64 v[222:223], s[18:19], 0, v[134:135]
	s_add_i32 m0, s79, 0x2000
	s_nop 0
	global_load_lds_dwordx4 v[222:223], off
	v_lshl_add_u64 v[222:223], s[62:63], 0, v[128:129]
	s_mov_b32 m0, s57
	s_nop 0
	global_load_lds_dwordx4 v[222:223], off
	s_mov_b32 m0, s67
	s_nop 0
	global_load_lds_dwordx4 v[224:225], off
	s_waitcnt vmcnt(8)
	s_waitcnt lgkmcnt(0)
	s_barrier
	s_setprio 1
	s_waitcnt lgkmcnt(0)
	v_mfma_f32_16x16x32_bf16 v[60:63], v[152:155], v[188:191], 0
	v_mfma_f32_16x16x32_bf16 v[60:63], v[156:159], v[192:195], v[60:63]
	v_mfma_f32_16x16x32_bf16 v[56:59], v[160:163], v[188:191], 0
	v_mfma_f32_16x16x32_bf16 v[56:59], v[164:167], v[192:195], v[56:59]
	v_mfma_f32_16x16x32_bf16 v[52:55], v[152:155], v[196:199], 0
	v_mfma_f32_16x16x32_bf16 v[52:55], v[156:159], v[200:203], v[52:55]
	v_mfma_f32_16x16x32_bf16 v[44:47], v[160:163], v[196:199], 0
	v_mfma_f32_16x16x32_bf16 v[44:47], v[164:167], v[200:203], v[44:47]
	v_mfma_f32_16x16x32_bf16 v[36:39], v[152:155], v[204:207], 0
	v_mfma_f32_16x16x32_bf16 v[36:39], v[156:159], v[208:211], v[36:39]
	v_mfma_f32_16x16x32_bf16 v[28:31], v[160:163], v[204:207], 0
	v_mfma_f32_16x16x32_bf16 v[28:31], v[164:167], v[208:211], v[28:31]
	v_mfma_f32_16x16x32_bf16 v[20:23], v[152:155], v[212:215], 0
	v_mfma_f32_16x16x32_bf16 v[20:23], v[156:159], v[216:219], v[20:23]
	v_mfma_f32_16x16x32_bf16 v[12:15], v[160:163], v[212:215], 0
	v_mfma_f32_16x16x32_bf16 v[12:15], v[164:167], v[216:219], v[12:15]
	v_mfma_f32_16x16x32_bf16 v[48:51], v[168:171], v[188:191], 0
	v_mfma_f32_16x16x32_bf16 v[48:51], v[172:175], v[192:195], v[48:51]
	v_mfma_f32_16x16x32_bf16 v[40:43], v[176:179], v[188:191], 0
	v_mfma_f32_16x16x32_bf16 v[40:43], v[184:187], v[192:195], v[40:43]
	v_mfma_f32_16x16x32_bf16 v[32:35], v[168:171], v[196:199], 0
	v_mfma_f32_16x16x32_bf16 v[32:35], v[172:175], v[200:203], v[32:35]
	v_mfma_f32_16x16x32_bf16 v[24:27], v[176:179], v[196:199], 0
	v_mfma_f32_16x16x32_bf16 v[24:27], v[184:187], v[200:203], v[24:27]
	v_mfma_f32_16x16x32_bf16 v[16:19], v[168:171], v[204:207], 0
	v_mfma_f32_16x16x32_bf16 v[16:19], v[172:175], v[208:211], v[16:19]
	v_mfma_f32_16x16x32_bf16 v[8:11], v[176:179], v[204:207], 0
	v_mfma_f32_16x16x32_bf16 v[8:11], v[184:187], v[208:211], v[8:11]
	v_mfma_f32_16x16x32_bf16 v[4:7], v[168:171], v[212:215], 0
	v_mfma_f32_16x16x32_bf16 v[4:7], v[172:175], v[216:219], v[4:7]
	v_mfma_f32_16x16x32_bf16 v[0:3], v[176:179], v[212:215], 0
	v_mfma_f32_16x16x32_bf16 v[0:3], v[184:187], v[216:219], v[0:3]
	s_setprio 0
	s_barrier
	s_branch .Lmid_gemm3
	.p2align	6

.LBB0_723:
	s_ashr_i32 s31, s30, 31
	s_lshl_b64 s[36:37], s[30:31], 19
	s_add_u32 s36, s80, s36
	s_addc_u32 s37, s81, s37
	s_and_b64 s[44:45], s[10:11], exec
	s_cselect_b32 s31, s37, s49
	s_cselect_b32 s70, s36, s48
	s_ashr_i32 s19, s18, 31
	s_lshl_b64 s[44:45], s[18:19], 19
	s_add_u32 s44, s56, s44
	s_addc_u32 s45, s57, s45
	s_and_b64 s[54:55], s[10:11], exec
	s_cselect_b32 s19, s45, s53
	s_cselect_b32 s71, s44, s52
	s_add_u32 s48, s48, 0x40080
	s_addc_u32 s49, s49, 0
	s_add_u32 s72, s52, 0x100
	s_addc_u32 s73, s53, 0
	s_mov_b32 s74, -2
	ds_read_b128 v[140:143], v147
	ds_read_b128 v[150:153], v147 offset:1024
	ds_read_b128 v[154:157], v147 offset:2048
	ds_read_b128 v[158:161], v147 offset:3072
	ds_read_b128 v[162:165], v148
	ds_read_b128 v[166:169], v148 offset:1024
	ds_read_b128 v[170:173], v148 offset:2048
	ds_read_b128 v[174:177], v148 offset:3072
	s_add_u32 s52, s48, 0xfffc0080
	s_addc_u32 s53, s49, -1
	s_cmp_eq_u32 s74, 12
	s_cselect_b32 s55, s31, s53
	s_cselect_b32 s54, s70, s52
	s_cselect_b32 s53, s19, s73
	s_cselect_b32 s52, s71, s72
	v_lshl_add_u64 v[178:179], s[48:49], 0, v[132:133]
	s_add_i32 m0, s47, 0xc000
	ds_read_b128 v[184:187], v149
	ds_read_b128 v[188:191], v149 offset:1024
	ds_read_b128 v[192:195], v149 offset:2048
	ds_read_b128 v[196:199], v149 offset:3072
	ds_read_b128 v[200:203], v149 offset:4096
	ds_read_b128 v[204:207], v149 offset:5120
	ds_read_b128 v[208:211], v149 offset:6144
	ds_read_b128 v[212:215], v149 offset:7168
	global_load_lds_dwordx4 v[178:179], off
	v_lshl_add_u64 v[178:179], s[48:49], 0, v[134:135]
	s_add_i32 m0, s47, 0xe000
	s_nop 0
	global_load_lds_dwordx4 v[178:179], off
	s_waitcnt vmcnt(8)
	s_waitcnt lgkmcnt(0)
	s_barrier
	s_setprio 1
	s_waitcnt lgkmcnt(0)
	v_mfma_f32_16x16x32_bf16 v[124:127], v[140:143], v[184:187], 0
	v_mfma_f32_16x16x32_bf16 v[124:127], v[150:153], v[188:191], v[124:127]
	v_mfma_f32_16x16x32_bf16 v[120:123], v[154:157], v[184:187], 0
	v_mfma_f32_16x16x32_bf16 v[120:123], v[158:161], v[188:191], v[120:123]
	v_mfma_f32_16x16x32_bf16 v[108:111], v[140:143], v[192:195], 0
	v_mfma_f32_16x16x32_bf16 v[108:111], v[150:153], v[196:199], v[108:111]
	v_mfma_f32_16x16x32_bf16 v[104:107], v[154:157], v[192:195], 0
	v_mfma_f32_16x16x32_bf16 v[104:107], v[158:161], v[196:199], v[104:107]
	v_mfma_f32_16x16x32_bf16 v[92:95], v[140:143], v[200:203], 0
	v_mfma_f32_16x16x32_bf16 v[92:95], v[150:153], v[204:207], v[92:95]
	v_mfma_f32_16x16x32_bf16 v[88:91], v[154:157], v[200:203], 0
	v_mfma_f32_16x16x32_bf16 v[88:91], v[158:161], v[204:207], v[88:91]
	v_mfma_f32_16x16x32_bf16 v[76:79], v[140:143], v[208:211], 0
	v_mfma_f32_16x16x32_bf16 v[76:79], v[150:153], v[212:215], v[76:79]
	v_mfma_f32_16x16x32_bf16 v[72:75], v[154:157], v[208:211], 0
	v_mfma_f32_16x16x32_bf16 v[72:75], v[158:161], v[212:215], v[72:75]
	v_mfma_f32_16x16x32_bf16 v[116:119], v[162:165], v[184:187], 0
	v_mfma_f32_16x16x32_bf16 v[116:119], v[166:169], v[188:191], v[116:119]
	v_mfma_f32_16x16x32_bf16 v[112:115], v[170:173], v[184:187], 0
	v_mfma_f32_16x16x32_bf16 v[112:115], v[174:177], v[188:191], v[112:115]
	v_mfma_f32_16x16x32_bf16 v[100:103], v[162:165], v[192:195], 0
	v_mfma_f32_16x16x32_bf16 v[100:103], v[166:169], v[196:199], v[100:103]
	v_mfma_f32_16x16x32_bf16 v[96:99], v[170:173], v[192:195], 0
	v_mfma_f32_16x16x32_bf16 v[96:99], v[174:177], v[196:199], v[96:99]
	v_mfma_f32_16x16x32_bf16 v[84:87], v[162:165], v[200:203], 0
	v_mfma_f32_16x16x32_bf16 v[84:87], v[166:169], v[204:207], v[84:87]
	v_mfma_f32_16x16x32_bf16 v[80:83], v[170:173], v[200:203], 0
	v_mfma_f32_16x16x32_bf16 v[80:83], v[174:177], v[204:207], v[80:83]
	v_mfma_f32_16x16x32_bf16 v[68:71], v[162:165], v[208:211], 0
	v_mfma_f32_16x16x32_bf16 v[68:71], v[166:169], v[212:215], v[68:71]
	v_mfma_f32_16x16x32_bf16 v[64:67], v[170:173], v[208:211], 0
	v_mfma_f32_16x16x32_bf16 v[64:67], v[174:177], v[212:215], v[64:67]
	s_setprio 0
	s_barrier
	s_add_i32 s75, s66, s58
	v_lshl_add_u64 v[178:179], s[52:53], 0, v[130:131]
	s_mov_b32 m0, s75
	ds_read_b128 v[184:187], v149 offset:16384
	ds_read_b128 v[188:191], v149 offset:17408
	ds_read_b128 v[192:195], v149 offset:18432
	ds_read_b128 v[196:199], v149 offset:19456
	ds_read_b128 v[200:203], v149 offset:20480
	ds_read_b128 v[204:207], v149 offset:21504
	ds_read_b128 v[208:211], v149 offset:22528
	ds_read_b128 v[212:215], v149 offset:23552
	global_load_lds_dwordx4 v[178:179], off
	s_add_i32 m0, s75, 0x2000
	s_add_u32 s76, s52, 0x40000
	v_lshl_add_u64 v[216:217], s[52:53], 0, v[128:129]
	s_addc_u32 s77, s53, 0
	s_add_i32 s75, s67, s58
	global_load_lds_dwordx4 v[216:217], off
	v_lshl_add_u64 v[218:219], s[76:77], 0, v[130:131]
	s_mov_b32 m0, s75
	v_lshl_add_u64 v[220:221], s[54:55], 0, v[128:129]
	global_load_lds_dwordx4 v[218:219], off
	v_lshl_add_u64 v[218:219], s[76:77], 0, v[128:129]
	s_add_i32 m0, s75, 0x2000
	s_nop 0
	global_load_lds_dwordx4 v[218:219], off
	v_lshl_add_u64 v[218:219], s[54:55], 0, v[130:131]
	s_mov_b32 m0, s47
	s_nop 0
	global_load_lds_dwordx4 v[218:219], off
	s_mov_b32 m0, s60
	s_nop 0
	global_load_lds_dwordx4 v[220:221], off
	s_waitcnt vmcnt(8)
	s_waitcnt lgkmcnt(0)
	s_barrier
	s_setprio 1
	s_waitcnt lgkmcnt(0)
	v_mfma_f32_16x16x32_bf16 v[60:63], v[140:143], v[184:187], 0
	v_mfma_f32_16x16x32_bf16 v[60:63], v[150:153], v[188:191], v[60:63]
	v_mfma_f32_16x16x32_bf16 v[56:59], v[154:157], v[184:187], 0
	v_mfma_f32_16x16x32_bf16 v[56:59], v[158:161], v[188:191], v[56:59]
	v_mfma_f32_16x16x32_bf16 v[44:47], v[140:143], v[192:195], 0
	v_mfma_f32_16x16x32_bf16 v[44:47], v[150:153], v[196:199], v[44:47]
	v_mfma_f32_16x16x32_bf16 v[40:43], v[154:157], v[192:195], 0
	v_mfma_f32_16x16x32_bf16 v[40:43], v[158:161], v[196:199], v[40:43]
	v_mfma_f32_16x16x32_bf16 v[28:31], v[140:143], v[200:203], 0
	v_mfma_f32_16x16x32_bf16 v[28:31], v[150:153], v[204:207], v[28:31]
	v_mfma_f32_16x16x32_bf16 v[24:27], v[154:157], v[200:203], 0
	v_mfma_f32_16x16x32_bf16 v[24:27], v[158:161], v[204:207], v[24:27]
	v_mfma_f32_16x16x32_bf16 v[12:15], v[140:143], v[208:211], 0
	v_mfma_f32_16x16x32_bf16 v[12:15], v[150:153], v[212:215], v[12:15]
	v_mfma_f32_16x16x32_bf16 v[8:11], v[154:157], v[208:211], 0
	v_mfma_f32_16x16x32_bf16 v[8:11], v[158:161], v[212:215], v[8:11]
	v_mfma_f32_16x16x32_bf16 v[52:55], v[162:165], v[184:187], 0
	v_mfma_f32_16x16x32_bf16 v[52:55], v[166:169], v[188:191], v[52:55]
	v_mfma_f32_16x16x32_bf16 v[48:51], v[170:173], v[184:187], 0
	v_mfma_f32_16x16x32_bf16 v[48:51], v[174:177], v[188:191], v[48:51]
	v_mfma_f32_16x16x32_bf16 v[36:39], v[162:165], v[192:195], 0
	v_mfma_f32_16x16x32_bf16 v[36:39], v[166:169], v[196:199], v[36:39]
	v_mfma_f32_16x16x32_bf16 v[32:35], v[170:173], v[192:195], 0
	v_mfma_f32_16x16x32_bf16 v[32:35], v[174:177], v[196:199], v[32:35]
	v_mfma_f32_16x16x32_bf16 v[20:23], v[162:165], v[200:203], 0
	v_mfma_f32_16x16x32_bf16 v[20:23], v[166:169], v[204:207], v[20:23]
	v_mfma_f32_16x16x32_bf16 v[16:19], v[170:173], v[200:203], 0
	v_mfma_f32_16x16x32_bf16 v[16:19], v[174:177], v[204:207], v[16:19]
	v_mfma_f32_16x16x32_bf16 v[4:7], v[162:165], v[208:211], 0
	v_mfma_f32_16x16x32_bf16 v[4:7], v[166:169], v[212:215], v[4:7]
	v_mfma_f32_16x16x32_bf16 v[0:3], v[170:173], v[208:211], 0
	v_mfma_f32_16x16x32_bf16 v[0:3], v[174:177], v[212:215], v[0:3]
	s_setprio 0
	s_barrier
	s_branch .Lmid_gemm4
	.p2align	6

.LBB0_803:
	s_add_u32 s84, s54, 0x100
	s_addc_u32 s85, s55, 0
	s_mov_b32 s86, -2
	ds_read_b128 v[152:155], v149
	ds_read_b128 v[156:159], v149 offset:1024
	ds_read_b128 v[160:163], v149 offset:2048
	ds_read_b128 v[164:167], v149 offset:3072
	ds_read_b128 v[168:171], v150
	ds_read_b128 v[172:175], v150 offset:1024
	ds_read_b128 v[176:179], v150 offset:2048
	ds_read_b128 v[184:187], v150 offset:3072
	s_add_u32 s54, s52, 0x100
	s_addc_u32 s55, s53, 0
	s_cmp_eq_u32 s86, 40
	s_cselect_b32 s59, s13, s55
	s_cselect_b32 s58, s12, s54
	s_cselect_b32 s57, s49, s85
	s_cselect_b32 s56, s48, s84
	v_lshl_add_u64 v[144:145], s[52:53], 0, v[136:137]
	s_add_i32 m0, s63, 0xc000
	ds_read_b128 v[188:191], v151
	ds_read_b128 v[192:195], v151 offset:1024
	ds_read_b128 v[196:199], v151 offset:2048
	ds_read_b128 v[200:203], v151 offset:3072
	ds_read_b128 v[204:207], v151 offset:4096
	ds_read_b128 v[208:211], v151 offset:5120
	ds_read_b128 v[212:215], v151 offset:6144
	ds_read_b128 v[216:219], v151 offset:7168
	global_load_lds_dwordx4 v[144:145], off
	v_lshl_add_u64 v[144:145], s[52:53], 0, v[138:139]
	s_add_i32 m0, s63, 0xe000
	s_nop 0
	global_load_lds_dwordx4 v[144:145], off
	s_waitcnt vmcnt(8)
	s_waitcnt lgkmcnt(0)
	s_barrier
	s_setprio 1
	s_waitcnt lgkmcnt(0)
	v_mfma_f32_16x16x32_bf16 v[124:127], v[152:155], v[188:191], 0
	v_mfma_f32_16x16x32_bf16 v[124:127], v[156:159], v[192:195], v[124:127]
	v_mfma_f32_16x16x32_bf16 v[120:123], v[160:163], v[188:191], 0
	v_mfma_f32_16x16x32_bf16 v[120:123], v[164:167], v[192:195], v[120:123]
	v_mfma_f32_16x16x32_bf16 v[116:119], v[152:155], v[196:199], 0
	v_mfma_f32_16x16x32_bf16 v[116:119], v[156:159], v[200:203], v[116:119]
	v_mfma_f32_16x16x32_bf16 v[108:111], v[160:163], v[196:199], 0
	v_mfma_f32_16x16x32_bf16 v[108:111], v[164:167], v[200:203], v[108:111]
	v_mfma_f32_16x16x32_bf16 v[100:103], v[152:155], v[204:207], 0
	v_mfma_f32_16x16x32_bf16 v[100:103], v[156:159], v[208:211], v[100:103]
	v_mfma_f32_16x16x32_bf16 v[92:95], v[160:163], v[204:207], 0
	v_mfma_f32_16x16x32_bf16 v[92:95], v[164:167], v[208:211], v[92:95]
	v_mfma_f32_16x16x32_bf16 v[84:87], v[152:155], v[212:215], 0
	v_mfma_f32_16x16x32_bf16 v[84:87], v[156:159], v[216:219], v[84:87]
	v_mfma_f32_16x16x32_bf16 v[76:79], v[160:163], v[212:215], 0
	v_mfma_f32_16x16x32_bf16 v[76:79], v[164:167], v[216:219], v[76:79]
	v_mfma_f32_16x16x32_bf16 v[112:115], v[168:171], v[188:191], 0
	v_mfma_f32_16x16x32_bf16 v[112:115], v[172:175], v[192:195], v[112:115]
	v_mfma_f32_16x16x32_bf16 v[104:107], v[176:179], v[188:191], 0
	v_mfma_f32_16x16x32_bf16 v[104:107], v[184:187], v[192:195], v[104:107]
	v_mfma_f32_16x16x32_bf16 v[96:99], v[168:171], v[196:199], 0
	v_mfma_f32_16x16x32_bf16 v[96:99], v[172:175], v[200:203], v[96:99]
	v_mfma_f32_16x16x32_bf16 v[88:91], v[176:179], v[196:199], 0
	v_mfma_f32_16x16x32_bf16 v[88:91], v[184:187], v[200:203], v[88:91]
	v_mfma_f32_16x16x32_bf16 v[80:83], v[168:171], v[204:207], 0
	v_mfma_f32_16x16x32_bf16 v[80:83], v[172:175], v[208:211], v[80:83]
	v_mfma_f32_16x16x32_bf16 v[72:75], v[176:179], v[204:207], 0
	v_mfma_f32_16x16x32_bf16 v[72:75], v[184:187], v[208:211], v[72:75]
	v_mfma_f32_16x16x32_bf16 v[68:71], v[168:171], v[212:215], 0
	v_mfma_f32_16x16x32_bf16 v[68:71], v[172:175], v[216:219], v[68:71]
	v_mfma_f32_16x16x32_bf16 v[64:67], v[176:179], v[212:215], 0
	v_mfma_f32_16x16x32_bf16 v[64:67], v[184:187], v[216:219], v[64:67]
	s_setprio 0
	s_barrier
	s_add_i32 s52, s70, s62
	v_lshl_add_u64 v[144:145], s[56:57], 0, v[130:131]
	s_mov_b32 m0, s52
	ds_read_b128 v[188:191], v151 offset:16384
	ds_read_b128 v[192:195], v151 offset:17408
	ds_read_b128 v[196:199], v151 offset:18432
	ds_read_b128 v[200:203], v151 offset:19456
	ds_read_b128 v[204:207], v151 offset:20480
	ds_read_b128 v[208:211], v151 offset:21504
	ds_read_b128 v[212:215], v151 offset:22528
	ds_read_b128 v[216:219], v151 offset:23552
	global_load_lds_dwordx4 v[144:145], off
	s_add_i32 m0, s52, 0x2000
	s_add_u32 s52, s56, 0xb0000
	v_lshl_add_u64 v[220:221], s[56:57], 0, v[134:135]
	s_addc_u32 s53, s57, 0
	s_add_i32 s79, s71, s62
	global_load_lds_dwordx4 v[220:221], off
	v_lshl_add_u64 v[222:223], s[52:53], 0, v[130:131]
	s_mov_b32 m0, s79
	v_lshl_add_u64 v[224:225], s[58:59], 0, v[132:133]
	global_load_lds_dwordx4 v[222:223], off
	v_lshl_add_u64 v[222:223], s[52:53], 0, v[134:135]
	s_add_i32 m0, s79, 0x2000
	s_nop 0
	global_load_lds_dwordx4 v[222:223], off
	v_lshl_add_u64 v[222:223], s[58:59], 0, v[128:129]
	s_mov_b32 m0, s63
	s_nop 0
	global_load_lds_dwordx4 v[222:223], off
	s_mov_b32 m0, s64
	s_nop 0
	global_load_lds_dwordx4 v[224:225], off
	s_waitcnt vmcnt(8)
	s_waitcnt lgkmcnt(0)
	s_barrier
	s_setprio 1
	s_waitcnt lgkmcnt(0)
	v_mfma_f32_16x16x32_bf16 v[60:63], v[152:155], v[188:191], 0
	v_mfma_f32_16x16x32_bf16 v[60:63], v[156:159], v[192:195], v[60:63]
	v_mfma_f32_16x16x32_bf16 v[56:59], v[160:163], v[188:191], 0
	v_mfma_f32_16x16x32_bf16 v[56:59], v[164:167], v[192:195], v[56:59]
	v_mfma_f32_16x16x32_bf16 v[52:55], v[152:155], v[196:199], 0
	v_mfma_f32_16x16x32_bf16 v[52:55], v[156:159], v[200:203], v[52:55]
	v_mfma_f32_16x16x32_bf16 v[44:47], v[160:163], v[196:199], 0
	v_mfma_f32_16x16x32_bf16 v[44:47], v[164:167], v[200:203], v[44:47]
	v_mfma_f32_16x16x32_bf16 v[36:39], v[152:155], v[204:207], 0
	v_mfma_f32_16x16x32_bf16 v[36:39], v[156:159], v[208:211], v[36:39]
	v_mfma_f32_16x16x32_bf16 v[28:31], v[160:163], v[204:207], 0
	v_mfma_f32_16x16x32_bf16 v[28:31], v[164:167], v[208:211], v[28:31]
	v_mfma_f32_16x16x32_bf16 v[20:23], v[152:155], v[212:215], 0
	v_mfma_f32_16x16x32_bf16 v[20:23], v[156:159], v[216:219], v[20:23]
	v_mfma_f32_16x16x32_bf16 v[12:15], v[160:163], v[212:215], 0
	v_mfma_f32_16x16x32_bf16 v[12:15], v[164:167], v[216:219], v[12:15]
	v_mfma_f32_16x16x32_bf16 v[48:51], v[168:171], v[188:191], 0
	v_mfma_f32_16x16x32_bf16 v[48:51], v[172:175], v[192:195], v[48:51]
	v_mfma_f32_16x16x32_bf16 v[40:43], v[176:179], v[188:191], 0
	v_mfma_f32_16x16x32_bf16 v[40:43], v[184:187], v[192:195], v[40:43]
	v_mfma_f32_16x16x32_bf16 v[32:35], v[168:171], v[196:199], 0
	v_mfma_f32_16x16x32_bf16 v[32:35], v[172:175], v[200:203], v[32:35]
	v_mfma_f32_16x16x32_bf16 v[24:27], v[176:179], v[196:199], 0
	v_mfma_f32_16x16x32_bf16 v[24:27], v[184:187], v[200:203], v[24:27]
	v_mfma_f32_16x16x32_bf16 v[16:19], v[168:171], v[204:207], 0
	v_mfma_f32_16x16x32_bf16 v[16:19], v[172:175], v[208:211], v[16:19]
	v_mfma_f32_16x16x32_bf16 v[8:11], v[176:179], v[204:207], 0
	v_mfma_f32_16x16x32_bf16 v[8:11], v[184:187], v[208:211], v[8:11]
	v_mfma_f32_16x16x32_bf16 v[4:7], v[168:171], v[212:215], 0
	v_mfma_f32_16x16x32_bf16 v[4:7], v[172:175], v[216:219], v[4:7]
	v_mfma_f32_16x16x32_bf16 v[0:3], v[176:179], v[212:215], 0
	v_mfma_f32_16x16x32_bf16 v[0:3], v[184:187], v[216:219], v[0:3]
	s_setprio 0
	s_barrier
	s_branch .Lmid_gemm5
	.p2align	6

.LBB0_934:
	s_ashr_i32 s53, s52, 31
	s_lshl_b64 s[54:55], s[52:53], 19
	s_add_u32 s54, s80, s54
	s_addc_u32 s55, s81, s55
	s_and_b64 s[56:57], s[10:11], exec
	s_cselect_b32 s53, s55, s61
	s_cselect_b32 s83, s54, s60
	s_ashr_i32 s49, s48, 31
	s_lshl_b64 s[56:57], s[48:49], 19
	s_add_u32 s56, s66, s56
	s_addc_u32 s57, s67, s57
	s_and_b64 s[64:65], s[10:11], exec
	s_cselect_b32 s49, s57, s63
	s_cselect_b32 s84, s56, s62
	s_add_u32 s60, s60, 0x40080
	s_addc_u32 s61, s61, 0
	s_add_u32 s85, s62, 0x100
	s_addc_u32 s86, s63, 0
	s_mov_b32 s87, -2
	ds_read_b128 v[152:155], v148
	ds_read_b128 v[156:159], v148 offset:1024
	ds_read_b128 v[160:163], v148 offset:2048
	ds_read_b128 v[164:167], v148 offset:3072
	ds_read_b128 v[168:171], v149
	ds_read_b128 v[172:175], v149 offset:1024
	ds_read_b128 v[176:179], v149 offset:2048
	ds_read_b128 v[184:187], v149 offset:3072
	s_add_u32 s62, s60, 0xfffc0080
	s_addc_u32 s63, s61, -1
	s_cmp_eq_u32 s87, 12
	s_cselect_b32 s65, s53, s63
	s_cselect_b32 s64, s83, s62
	s_cselect_b32 s63, s49, s86
	s_cselect_b32 s62, s84, s85
	v_lshl_add_u64 v[220:221], s[60:61], 0, v[138:139]
	s_add_i32 m0, s69, 0xc000
	ds_read_b128 v[188:191], v150
	ds_read_b128 v[192:195], v150 offset:1024
	ds_read_b128 v[196:199], v150 offset:2048
	ds_read_b128 v[200:203], v150 offset:3072
	ds_read_b128 v[204:207], v150 offset:4096
	ds_read_b128 v[208:211], v150 offset:5120
	ds_read_b128 v[212:215], v150 offset:6144
	ds_read_b128 v[216:219], v150 offset:7168
	global_load_lds_dwordx4 v[220:221], off
	v_lshl_add_u64 v[220:221], s[60:61], 0, v[140:141]
	s_add_i32 m0, s69, 0xe000
	s_nop 0
	global_load_lds_dwordx4 v[220:221], off
	s_waitcnt vmcnt(8)
	s_waitcnt lgkmcnt(0)
	s_barrier
	s_setprio 1
	s_waitcnt lgkmcnt(0)
	v_mfma_f32_16x16x32_bf16 v[124:127], v[152:155], v[188:191], 0
	v_mfma_f32_16x16x32_bf16 v[124:127], v[156:159], v[192:195], v[124:127]
	v_mfma_f32_16x16x32_bf16 v[120:123], v[160:163], v[188:191], 0
	v_mfma_f32_16x16x32_bf16 v[120:123], v[164:167], v[192:195], v[120:123]
	v_mfma_f32_16x16x32_bf16 v[116:119], v[152:155], v[196:199], 0
	v_mfma_f32_16x16x32_bf16 v[116:119], v[156:159], v[200:203], v[116:119]
	v_mfma_f32_16x16x32_bf16 v[112:115], v[160:163], v[196:199], 0
	v_mfma_f32_16x16x32_bf16 v[112:115], v[164:167], v[200:203], v[112:115]
	v_mfma_f32_16x16x32_bf16 v[108:111], v[152:155], v[204:207], 0
	v_mfma_f32_16x16x32_bf16 v[108:111], v[156:159], v[208:211], v[108:111]
	v_mfma_f32_16x16x32_bf16 v[104:107], v[160:163], v[204:207], 0
	v_mfma_f32_16x16x32_bf16 v[104:107], v[164:167], v[208:211], v[104:107]
	v_mfma_f32_16x16x32_bf16 v[100:103], v[152:155], v[212:215], 0
	v_mfma_f32_16x16x32_bf16 v[100:103], v[156:159], v[216:219], v[100:103]
	v_mfma_f32_16x16x32_bf16 v[96:99], v[160:163], v[212:215], 0
	v_mfma_f32_16x16x32_bf16 v[96:99], v[164:167], v[216:219], v[96:99]
	v_mfma_f32_16x16x32_bf16 v[76:79], v[168:171], v[188:191], 0
	v_mfma_f32_16x16x32_bf16 v[76:79], v[172:175], v[192:195], v[76:79]
	v_mfma_f32_16x16x32_bf16 v[68:71], v[176:179], v[188:191], 0
	v_mfma_f32_16x16x32_bf16 v[68:71], v[184:187], v[192:195], v[68:71]
	v_mfma_f32_16x16x32_bf16 v[60:63], v[168:171], v[196:199], 0
	v_mfma_f32_16x16x32_bf16 v[60:63], v[172:175], v[200:203], v[60:63]
	v_mfma_f32_16x16x32_bf16 v[52:55], v[176:179], v[196:199], 0
	v_mfma_f32_16x16x32_bf16 v[52:55], v[184:187], v[200:203], v[52:55]
	v_mfma_f32_16x16x32_bf16 v[44:47], v[168:171], v[204:207], 0
	v_mfma_f32_16x16x32_bf16 v[44:47], v[172:175], v[208:211], v[44:47]
	v_mfma_f32_16x16x32_bf16 v[40:43], v[176:179], v[204:207], 0
	v_mfma_f32_16x16x32_bf16 v[40:43], v[184:187], v[208:211], v[40:43]
	v_mfma_f32_16x16x32_bf16 v[36:39], v[168:171], v[212:215], 0
	v_mfma_f32_16x16x32_bf16 v[36:39], v[172:175], v[216:219], v[36:39]
	v_mfma_f32_16x16x32_bf16 v[32:35], v[176:179], v[212:215], 0
	v_mfma_f32_16x16x32_bf16 v[32:35], v[184:187], v[216:219], v[32:35]
	s_setprio 0
	s_barrier
	s_add_i32 s79, s77, s68
	v_lshl_add_u64 v[220:221], s[62:63], 0, v[130:131]
	s_mov_b32 m0, s79
	ds_read_b128 v[188:191], v150 offset:16384
	ds_read_b128 v[192:195], v150 offset:17408
	ds_read_b128 v[196:199], v150 offset:18432
	ds_read_b128 v[200:203], v150 offset:19456
	ds_read_b128 v[204:207], v150 offset:20480
	ds_read_b128 v[208:211], v150 offset:21504
	ds_read_b128 v[212:215], v150 offset:22528
	ds_read_b128 v[216:219], v150 offset:23552
	global_load_lds_dwordx4 v[220:221], off
	s_add_i32 m0, s79, 0x2000
	s_add_u32 s88, s62, 0x40000
	v_lshl_add_u64 v[222:223], s[62:63], 0, v[134:135]
	s_addc_u32 s89, s63, 0
	s_add_i32 s79, s82, s68
	global_load_lds_dwordx4 v[222:223], off
	v_lshl_add_u64 v[224:225], s[88:89], 0, v[130:131]
	s_mov_b32 m0, s79
	v_lshl_add_u64 v[226:227], s[64:65], 0, v[132:133]
	global_load_lds_dwordx4 v[224:225], off
	v_lshl_add_u64 v[224:225], s[88:89], 0, v[134:135]
	s_add_i32 m0, s79, 0x2000
	s_nop 0
	global_load_lds_dwordx4 v[224:225], off
	v_lshl_add_u64 v[224:225], s[64:65], 0, v[128:129]
	s_mov_b32 m0, s69
	s_nop 0
	global_load_lds_dwordx4 v[224:225], off
	s_mov_b32 m0, s70
	s_nop 0
	global_load_lds_dwordx4 v[226:227], off
	s_waitcnt vmcnt(8)
	s_waitcnt lgkmcnt(0)
	s_barrier
	s_setprio 1
	s_waitcnt lgkmcnt(0)
	v_mfma_f32_16x16x32_bf16 v[92:95], v[152:155], v[188:191], 0
	v_mfma_f32_16x16x32_bf16 v[92:95], v[156:159], v[192:195], v[92:95]
	v_mfma_f32_16x16x32_bf16 v[88:91], v[160:163], v[188:191], 0
	v_mfma_f32_16x16x32_bf16 v[88:91], v[164:167], v[192:195], v[88:91]
	v_mfma_f32_16x16x32_bf16 v[84:87], v[152:155], v[196:199], 0
	v_mfma_f32_16x16x32_bf16 v[84:87], v[156:159], v[200:203], v[84:87]
	v_mfma_f32_16x16x32_bf16 v[80:83], v[160:163], v[196:199], 0
	v_mfma_f32_16x16x32_bf16 v[80:83], v[164:167], v[200:203], v[80:83]
	v_mfma_f32_16x16x32_bf16 v[72:75], v[152:155], v[204:207], 0
	v_mfma_f32_16x16x32_bf16 v[72:75], v[156:159], v[208:211], v[72:75]
	v_mfma_f32_16x16x32_bf16 v[64:67], v[160:163], v[204:207], 0
	v_mfma_f32_16x16x32_bf16 v[64:67], v[164:167], v[208:211], v[64:67]
	v_mfma_f32_16x16x32_bf16 v[56:59], v[152:155], v[212:215], 0
	v_mfma_f32_16x16x32_bf16 v[56:59], v[156:159], v[216:219], v[56:59]
	v_mfma_f32_16x16x32_bf16 v[48:51], v[160:163], v[212:215], 0
	v_mfma_f32_16x16x32_bf16 v[48:51], v[164:167], v[216:219], v[48:51]
	v_mfma_f32_16x16x32_bf16 v[28:31], v[168:171], v[188:191], 0
	v_mfma_f32_16x16x32_bf16 v[28:31], v[172:175], v[192:195], v[28:31]
	v_mfma_f32_16x16x32_bf16 v[24:27], v[176:179], v[188:191], 0
	v_mfma_f32_16x16x32_bf16 v[24:27], v[184:187], v[192:195], v[24:27]
	v_mfma_f32_16x16x32_bf16 v[20:23], v[168:171], v[196:199], 0
	v_mfma_f32_16x16x32_bf16 v[20:23], v[172:175], v[200:203], v[20:23]
	v_mfma_f32_16x16x32_bf16 v[16:19], v[176:179], v[196:199], 0
	v_mfma_f32_16x16x32_bf16 v[16:19], v[184:187], v[200:203], v[16:19]
	v_mfma_f32_16x16x32_bf16 v[12:15], v[168:171], v[204:207], 0
	v_mfma_f32_16x16x32_bf16 v[12:15], v[172:175], v[208:211], v[12:15]
	v_mfma_f32_16x16x32_bf16 v[8:11], v[176:179], v[204:207], 0
	v_mfma_f32_16x16x32_bf16 v[8:11], v[184:187], v[208:211], v[8:11]
	v_mfma_f32_16x16x32_bf16 v[4:7], v[168:171], v[212:215], 0
	v_mfma_f32_16x16x32_bf16 v[4:7], v[172:175], v[216:219], v[4:7]
	v_mfma_f32_16x16x32_bf16 v[0:3], v[176:179], v[212:215], 0
	v_mfma_f32_16x16x32_bf16 v[0:3], v[184:187], v[216:219], v[0:3]
	s_setprio 0
	s_barrier
	s_branch .Lmid_gemm6
	.p2align	6

.LBB0_950:
	s_ashr_i32 s37, s36, 31
	s_lshl_b64 s[44:45], s[36:37], 19
	s_add_u32 s44, s80, s44
	s_addc_u32 s45, s81, s45
	s_and_b64 s[46:47], s[10:11], exec
	s_cselect_b32 s37, s45, s53
	s_cselect_b32 s72, s44, s52
	s_ashr_i32 s19, s18, 31
	s_lshl_b64 s[46:47], s[18:19], 19
	s_add_u32 s46, s58, s46
	s_addc_u32 s47, s59, s47
	s_and_b64 s[56:57], s[10:11], exec
	s_cselect_b32 s19, s47, s55
	s_cselect_b32 s73, s46, s54
	s_add_u32 s52, s52, 0x40080
	s_addc_u32 s53, s53, 0
	s_add_u32 s74, s54, 0x100
	s_addc_u32 s75, s55, 0
	s_mov_b32 s76, -2
	ds_read_b128 v[140:143], v147
	ds_read_b128 v[150:153], v147 offset:1024
	ds_read_b128 v[154:157], v147 offset:2048
	ds_read_b128 v[158:161], v147 offset:3072
	ds_read_b128 v[162:165], v148
	ds_read_b128 v[166:169], v148 offset:1024
	ds_read_b128 v[170:173], v148 offset:2048
	ds_read_b128 v[174:177], v148 offset:3072
	s_add_u32 s54, s52, 0xfffc0080
	s_addc_u32 s55, s53, -1
	s_cmp_eq_u32 s76, 12
	s_cselect_b32 s57, s37, s55
	s_cselect_b32 s56, s72, s54
	s_cselect_b32 s55, s19, s75
	s_cselect_b32 s54, s73, s74
	v_lshl_add_u64 v[178:179], s[52:53], 0, v[132:133]
	s_add_i32 m0, s49, 0xc000
	ds_read_b128 v[184:187], v149
	ds_read_b128 v[188:191], v149 offset:1024
	ds_read_b128 v[192:195], v149 offset:2048
	ds_read_b128 v[196:199], v149 offset:3072
	ds_read_b128 v[200:203], v149 offset:4096
	ds_read_b128 v[204:207], v149 offset:5120
	ds_read_b128 v[208:211], v149 offset:6144
	ds_read_b128 v[212:215], v149 offset:7168
	global_load_lds_dwordx4 v[178:179], off
	v_lshl_add_u64 v[178:179], s[52:53], 0, v[134:135]
	s_add_i32 m0, s49, 0xe000
	s_nop 0
	global_load_lds_dwordx4 v[178:179], off
	s_waitcnt vmcnt(8)
	s_waitcnt lgkmcnt(0)
	s_barrier
	s_setprio 1
	s_waitcnt lgkmcnt(0)
	v_mfma_f32_16x16x32_bf16 v[124:127], v[140:143], v[184:187], 0
	v_mfma_f32_16x16x32_bf16 v[124:127], v[150:153], v[188:191], v[124:127]
	v_mfma_f32_16x16x32_bf16 v[120:123], v[154:157], v[184:187], 0
	v_mfma_f32_16x16x32_bf16 v[120:123], v[158:161], v[188:191], v[120:123]
	v_mfma_f32_16x16x32_bf16 v[108:111], v[140:143], v[192:195], 0
	v_mfma_f32_16x16x32_bf16 v[108:111], v[150:153], v[196:199], v[108:111]
	v_mfma_f32_16x16x32_bf16 v[104:107], v[154:157], v[192:195], 0
	v_mfma_f32_16x16x32_bf16 v[104:107], v[158:161], v[196:199], v[104:107]
	v_mfma_f32_16x16x32_bf16 v[92:95], v[140:143], v[200:203], 0
	v_mfma_f32_16x16x32_bf16 v[92:95], v[150:153], v[204:207], v[92:95]
	v_mfma_f32_16x16x32_bf16 v[88:91], v[154:157], v[200:203], 0
	v_mfma_f32_16x16x32_bf16 v[88:91], v[158:161], v[204:207], v[88:91]
	v_mfma_f32_16x16x32_bf16 v[76:79], v[140:143], v[208:211], 0
	v_mfma_f32_16x16x32_bf16 v[76:79], v[150:153], v[212:215], v[76:79]
	v_mfma_f32_16x16x32_bf16 v[72:75], v[154:157], v[208:211], 0
	v_mfma_f32_16x16x32_bf16 v[72:75], v[158:161], v[212:215], v[72:75]
	v_mfma_f32_16x16x32_bf16 v[116:119], v[162:165], v[184:187], 0
	v_mfma_f32_16x16x32_bf16 v[116:119], v[166:169], v[188:191], v[116:119]
	v_mfma_f32_16x16x32_bf16 v[112:115], v[170:173], v[184:187], 0
	v_mfma_f32_16x16x32_bf16 v[112:115], v[174:177], v[188:191], v[112:115]
	v_mfma_f32_16x16x32_bf16 v[100:103], v[162:165], v[192:195], 0
	v_mfma_f32_16x16x32_bf16 v[100:103], v[166:169], v[196:199], v[100:103]
	v_mfma_f32_16x16x32_bf16 v[96:99], v[170:173], v[192:195], 0
	v_mfma_f32_16x16x32_bf16 v[96:99], v[174:177], v[196:199], v[96:99]
	v_mfma_f32_16x16x32_bf16 v[84:87], v[162:165], v[200:203], 0
	v_mfma_f32_16x16x32_bf16 v[84:87], v[166:169], v[204:207], v[84:87]
	v_mfma_f32_16x16x32_bf16 v[80:83], v[170:173], v[200:203], 0
	v_mfma_f32_16x16x32_bf16 v[80:83], v[174:177], v[204:207], v[80:83]
	v_mfma_f32_16x16x32_bf16 v[68:71], v[162:165], v[208:211], 0
	v_mfma_f32_16x16x32_bf16 v[68:71], v[166:169], v[212:215], v[68:71]
	v_mfma_f32_16x16x32_bf16 v[64:67], v[170:173], v[208:211], 0
	v_mfma_f32_16x16x32_bf16 v[64:67], v[174:177], v[212:215], v[64:67]
	s_setprio 0
	s_barrier
	s_add_i32 s77, s68, s60
	v_lshl_add_u64 v[178:179], s[54:55], 0, v[130:131]
	s_mov_b32 m0, s77
	ds_read_b128 v[184:187], v149 offset:16384
	ds_read_b128 v[188:191], v149 offset:17408
	ds_read_b128 v[192:195], v149 offset:18432
	ds_read_b128 v[196:199], v149 offset:19456
	ds_read_b128 v[200:203], v149 offset:20480
	ds_read_b128 v[204:207], v149 offset:21504
	ds_read_b128 v[208:211], v149 offset:22528
	ds_read_b128 v[212:215], v149 offset:23552
	global_load_lds_dwordx4 v[178:179], off
	s_add_i32 m0, s77, 0x2000
	s_add_u32 s82, s54, 0x40000
	v_lshl_add_u64 v[216:217], s[54:55], 0, v[128:129]
	s_addc_u32 s83, s55, 0
	s_add_i32 s77, s69, s60
	global_load_lds_dwordx4 v[216:217], off
	v_lshl_add_u64 v[218:219], s[82:83], 0, v[130:131]
	s_mov_b32 m0, s77
	v_lshl_add_u64 v[220:221], s[56:57], 0, v[128:129]
	global_load_lds_dwordx4 v[218:219], off
	v_lshl_add_u64 v[218:219], s[82:83], 0, v[128:129]
	s_add_i32 m0, s77, 0x2000
	s_nop 0
	global_load_lds_dwordx4 v[218:219], off
	v_lshl_add_u64 v[218:219], s[56:57], 0, v[130:131]
	s_mov_b32 m0, s49
	s_nop 0
	global_load_lds_dwordx4 v[218:219], off
	s_mov_b32 m0, s62
	s_nop 0
	global_load_lds_dwordx4 v[220:221], off
	s_waitcnt vmcnt(8)
	s_waitcnt lgkmcnt(0)
	s_barrier
	s_setprio 1
	s_waitcnt lgkmcnt(0)
	v_mfma_f32_16x16x32_bf16 v[60:63], v[140:143], v[184:187], 0
	v_mfma_f32_16x16x32_bf16 v[60:63], v[150:153], v[188:191], v[60:63]
	v_mfma_f32_16x16x32_bf16 v[56:59], v[154:157], v[184:187], 0
	v_mfma_f32_16x16x32_bf16 v[56:59], v[158:161], v[188:191], v[56:59]
	v_mfma_f32_16x16x32_bf16 v[44:47], v[140:143], v[192:195], 0
	v_mfma_f32_16x16x32_bf16 v[44:47], v[150:153], v[196:199], v[44:47]
	v_mfma_f32_16x16x32_bf16 v[40:43], v[154:157], v[192:195], 0
	v_mfma_f32_16x16x32_bf16 v[40:43], v[158:161], v[196:199], v[40:43]
	v_mfma_f32_16x16x32_bf16 v[28:31], v[140:143], v[200:203], 0
	v_mfma_f32_16x16x32_bf16 v[28:31], v[150:153], v[204:207], v[28:31]
	v_mfma_f32_16x16x32_bf16 v[24:27], v[154:157], v[200:203], 0
	v_mfma_f32_16x16x32_bf16 v[24:27], v[158:161], v[204:207], v[24:27]
	v_mfma_f32_16x16x32_bf16 v[12:15], v[140:143], v[208:211], 0
	v_mfma_f32_16x16x32_bf16 v[12:15], v[150:153], v[212:215], v[12:15]
	v_mfma_f32_16x16x32_bf16 v[8:11], v[154:157], v[208:211], 0
	v_mfma_f32_16x16x32_bf16 v[8:11], v[158:161], v[212:215], v[8:11]
	v_mfma_f32_16x16x32_bf16 v[52:55], v[162:165], v[184:187], 0
	v_mfma_f32_16x16x32_bf16 v[52:55], v[166:169], v[188:191], v[52:55]
	v_mfma_f32_16x16x32_bf16 v[48:51], v[170:173], v[184:187], 0
	v_mfma_f32_16x16x32_bf16 v[48:51], v[174:177], v[188:191], v[48:51]
	v_mfma_f32_16x16x32_bf16 v[36:39], v[162:165], v[192:195], 0
	v_mfma_f32_16x16x32_bf16 v[36:39], v[166:169], v[196:199], v[36:39]
	v_mfma_f32_16x16x32_bf16 v[32:35], v[170:173], v[192:195], 0
	v_mfma_f32_16x16x32_bf16 v[32:35], v[174:177], v[196:199], v[32:35]
	v_mfma_f32_16x16x32_bf16 v[20:23], v[162:165], v[200:203], 0
	v_mfma_f32_16x16x32_bf16 v[20:23], v[166:169], v[204:207], v[20:23]
	v_mfma_f32_16x16x32_bf16 v[16:19], v[170:173], v[200:203], 0
	v_mfma_f32_16x16x32_bf16 v[16:19], v[174:177], v[204:207], v[16:19]
	v_mfma_f32_16x16x32_bf16 v[4:7], v[162:165], v[208:211], 0
	v_mfma_f32_16x16x32_bf16 v[4:7], v[166:169], v[212:215], v[4:7]
	v_mfma_f32_16x16x32_bf16 v[0:3], v[170:173], v[208:211], 0
	v_mfma_f32_16x16x32_bf16 v[0:3], v[174:177], v[212:215], v[0:3]
	s_setprio 0
	s_barrier
	s_branch .Lmid_gemm7
	.p2align	6

.LBB0_1030:
	s_add_u32 s86, s56, 0x100
	s_addc_u32 s87, s57, 0
	s_mov_b32 s88, -2
	ds_read_b128 v[152:155], v149
	ds_read_b128 v[156:159], v149 offset:1024
	ds_read_b128 v[160:163], v149 offset:2048
	ds_read_b128 v[164:167], v149 offset:3072
	ds_read_b128 v[168:171], v150
	ds_read_b128 v[172:175], v150 offset:1024
	ds_read_b128 v[176:179], v150 offset:2048
	ds_read_b128 v[184:187], v150 offset:3072
	s_add_u32 s56, s54, 0x100
	s_addc_u32 s57, s55, 0
	s_cmp_eq_u32 s88, 40
	s_cselect_b32 s61, s13, s57
	s_cselect_b32 s60, s12, s56
	s_cselect_b32 s59, s53, s87
	s_cselect_b32 s58, s52, s86
	v_lshl_add_u64 v[144:145], s[54:55], 0, v[136:137]
	s_add_i32 m0, s65, 0xc000
	ds_read_b128 v[188:191], v151
	ds_read_b128 v[192:195], v151 offset:1024
	ds_read_b128 v[196:199], v151 offset:2048
	ds_read_b128 v[200:203], v151 offset:3072
	ds_read_b128 v[204:207], v151 offset:4096
	ds_read_b128 v[208:211], v151 offset:5120
	ds_read_b128 v[212:215], v151 offset:6144
	ds_read_b128 v[216:219], v151 offset:7168
	global_load_lds_dwordx4 v[144:145], off
	v_lshl_add_u64 v[144:145], s[54:55], 0, v[138:139]
	s_add_i32 m0, s65, 0xe000
	s_nop 0
	global_load_lds_dwordx4 v[144:145], off
	s_waitcnt vmcnt(8)
	s_waitcnt lgkmcnt(0)
	s_barrier
	s_setprio 1
	s_waitcnt lgkmcnt(0)
	v_mfma_f32_16x16x32_bf16 v[124:127], v[152:155], v[188:191], 0
	v_mfma_f32_16x16x32_bf16 v[124:127], v[156:159], v[192:195], v[124:127]
	v_mfma_f32_16x16x32_bf16 v[120:123], v[160:163], v[188:191], 0
	v_mfma_f32_16x16x32_bf16 v[120:123], v[164:167], v[192:195], v[120:123]
	v_mfma_f32_16x16x32_bf16 v[116:119], v[152:155], v[196:199], 0
	v_mfma_f32_16x16x32_bf16 v[116:119], v[156:159], v[200:203], v[116:119]
	v_mfma_f32_16x16x32_bf16 v[108:111], v[160:163], v[196:199], 0
	v_mfma_f32_16x16x32_bf16 v[108:111], v[164:167], v[200:203], v[108:111]
	v_mfma_f32_16x16x32_bf16 v[100:103], v[152:155], v[204:207], 0
	v_mfma_f32_16x16x32_bf16 v[100:103], v[156:159], v[208:211], v[100:103]
	v_mfma_f32_16x16x32_bf16 v[92:95], v[160:163], v[204:207], 0
	v_mfma_f32_16x16x32_bf16 v[92:95], v[164:167], v[208:211], v[92:95]
	v_mfma_f32_16x16x32_bf16 v[84:87], v[152:155], v[212:215], 0
	v_mfma_f32_16x16x32_bf16 v[84:87], v[156:159], v[216:219], v[84:87]
	v_mfma_f32_16x16x32_bf16 v[76:79], v[160:163], v[212:215], 0
	v_mfma_f32_16x16x32_bf16 v[76:79], v[164:167], v[216:219], v[76:79]
	v_mfma_f32_16x16x32_bf16 v[112:115], v[168:171], v[188:191], 0
	v_mfma_f32_16x16x32_bf16 v[112:115], v[172:175], v[192:195], v[112:115]
	v_mfma_f32_16x16x32_bf16 v[104:107], v[176:179], v[188:191], 0
	v_mfma_f32_16x16x32_bf16 v[104:107], v[184:187], v[192:195], v[104:107]
	v_mfma_f32_16x16x32_bf16 v[96:99], v[168:171], v[196:199], 0
	v_mfma_f32_16x16x32_bf16 v[96:99], v[172:175], v[200:203], v[96:99]
	v_mfma_f32_16x16x32_bf16 v[88:91], v[176:179], v[196:199], 0
	v_mfma_f32_16x16x32_bf16 v[88:91], v[184:187], v[200:203], v[88:91]
	v_mfma_f32_16x16x32_bf16 v[80:83], v[168:171], v[204:207], 0
	v_mfma_f32_16x16x32_bf16 v[80:83], v[172:175], v[208:211], v[80:83]
	v_mfma_f32_16x16x32_bf16 v[72:75], v[176:179], v[204:207], 0
	v_mfma_f32_16x16x32_bf16 v[72:75], v[184:187], v[208:211], v[72:75]
	v_mfma_f32_16x16x32_bf16 v[68:71], v[168:171], v[212:215], 0
	v_mfma_f32_16x16x32_bf16 v[68:71], v[172:175], v[216:219], v[68:71]
	v_mfma_f32_16x16x32_bf16 v[64:67], v[176:179], v[212:215], 0
	v_mfma_f32_16x16x32_bf16 v[64:67], v[184:187], v[216:219], v[64:67]
	s_setprio 0
	s_barrier
	s_add_i32 s54, s72, s64
	v_lshl_add_u64 v[144:145], s[58:59], 0, v[130:131]
	s_mov_b32 m0, s54
	ds_read_b128 v[188:191], v151 offset:16384
	ds_read_b128 v[192:195], v151 offset:17408
	ds_read_b128 v[196:199], v151 offset:18432
	ds_read_b128 v[200:203], v151 offset:19456
	ds_read_b128 v[204:207], v151 offset:20480
	ds_read_b128 v[208:211], v151 offset:21504
	ds_read_b128 v[212:215], v151 offset:22528
	ds_read_b128 v[216:219], v151 offset:23552
	global_load_lds_dwordx4 v[144:145], off
	s_add_i32 m0, s54, 0x2000
	s_add_u32 s54, s58, 0xb0000
	v_lshl_add_u64 v[220:221], s[58:59], 0, v[134:135]
	s_addc_u32 s55, s59, 0
	s_add_i32 s79, s73, s64
	global_load_lds_dwordx4 v[220:221], off
	v_lshl_add_u64 v[222:223], s[54:55], 0, v[130:131]
	s_mov_b32 m0, s79
	v_lshl_add_u64 v[224:225], s[60:61], 0, v[132:133]
	global_load_lds_dwordx4 v[222:223], off
	v_lshl_add_u64 v[222:223], s[54:55], 0, v[134:135]
	s_add_i32 m0, s79, 0x2000
	s_nop 0
	global_load_lds_dwordx4 v[222:223], off
	v_lshl_add_u64 v[222:223], s[60:61], 0, v[128:129]
	s_mov_b32 m0, s65
	s_nop 0
	global_load_lds_dwordx4 v[222:223], off
	s_mov_b32 m0, s66
	s_nop 0
	global_load_lds_dwordx4 v[224:225], off
	s_waitcnt vmcnt(8)
	s_waitcnt lgkmcnt(0)
	s_barrier
	s_setprio 1
	s_waitcnt lgkmcnt(0)
	v_mfma_f32_16x16x32_bf16 v[60:63], v[152:155], v[188:191], 0
	v_mfma_f32_16x16x32_bf16 v[60:63], v[156:159], v[192:195], v[60:63]
	v_mfma_f32_16x16x32_bf16 v[56:59], v[160:163], v[188:191], 0
	v_mfma_f32_16x16x32_bf16 v[56:59], v[164:167], v[192:195], v[56:59]
	v_mfma_f32_16x16x32_bf16 v[52:55], v[152:155], v[196:199], 0
	v_mfma_f32_16x16x32_bf16 v[52:55], v[156:159], v[200:203], v[52:55]
	v_mfma_f32_16x16x32_bf16 v[44:47], v[160:163], v[196:199], 0
	v_mfma_f32_16x16x32_bf16 v[44:47], v[164:167], v[200:203], v[44:47]
	v_mfma_f32_16x16x32_bf16 v[36:39], v[152:155], v[204:207], 0
	v_mfma_f32_16x16x32_bf16 v[36:39], v[156:159], v[208:211], v[36:39]
	v_mfma_f32_16x16x32_bf16 v[28:31], v[160:163], v[204:207], 0
	v_mfma_f32_16x16x32_bf16 v[28:31], v[164:167], v[208:211], v[28:31]
	v_mfma_f32_16x16x32_bf16 v[20:23], v[152:155], v[212:215], 0
	v_mfma_f32_16x16x32_bf16 v[20:23], v[156:159], v[216:219], v[20:23]
	v_mfma_f32_16x16x32_bf16 v[12:15], v[160:163], v[212:215], 0
	v_mfma_f32_16x16x32_bf16 v[12:15], v[164:167], v[216:219], v[12:15]
	v_mfma_f32_16x16x32_bf16 v[48:51], v[168:171], v[188:191], 0
	v_mfma_f32_16x16x32_bf16 v[48:51], v[172:175], v[192:195], v[48:51]
	v_mfma_f32_16x16x32_bf16 v[40:43], v[176:179], v[188:191], 0
	v_mfma_f32_16x16x32_bf16 v[40:43], v[184:187], v[192:195], v[40:43]
	v_mfma_f32_16x16x32_bf16 v[32:35], v[168:171], v[196:199], 0
	v_mfma_f32_16x16x32_bf16 v[32:35], v[172:175], v[200:203], v[32:35]
	v_mfma_f32_16x16x32_bf16 v[24:27], v[176:179], v[196:199], 0
	v_mfma_f32_16x16x32_bf16 v[24:27], v[184:187], v[200:203], v[24:27]
	v_mfma_f32_16x16x32_bf16 v[16:19], v[168:171], v[204:207], 0
	v_mfma_f32_16x16x32_bf16 v[16:19], v[172:175], v[208:211], v[16:19]
	v_mfma_f32_16x16x32_bf16 v[8:11], v[176:179], v[204:207], 0
	v_mfma_f32_16x16x32_bf16 v[8:11], v[184:187], v[208:211], v[8:11]
	v_mfma_f32_16x16x32_bf16 v[4:7], v[168:171], v[212:215], 0
	v_mfma_f32_16x16x32_bf16 v[4:7], v[172:175], v[216:219], v[4:7]
	v_mfma_f32_16x16x32_bf16 v[0:3], v[176:179], v[212:215], 0
	v_mfma_f32_16x16x32_bf16 v[0:3], v[184:187], v[216:219], v[0:3]
	s_setprio 0
	s_barrier
	s_branch .Lmid_gemm8
	.p2align	6

.LBB0_1161:
	s_ashr_i32 s53, s52, 31
	s_lshl_b64 s[54:55], s[52:53], 19
	s_add_u32 s54, s80, s54
	s_addc_u32 s55, s81, s55
	s_and_b64 s[56:57], s[10:11], exec
	s_cselect_b32 s53, s55, s61
	s_cselect_b32 s83, s54, s60
	s_ashr_i32 s49, s48, 31
	s_lshl_b64 s[56:57], s[48:49], 19
	s_add_u32 s56, s66, s56
	s_addc_u32 s57, s67, s57
	s_and_b64 s[64:65], s[10:11], exec
	s_cselect_b32 s49, s57, s63
	s_cselect_b32 s84, s56, s62
	s_add_u32 s60, s60, 0x40080
	s_addc_u32 s61, s61, 0
	s_add_u32 s85, s62, 0x100
	s_addc_u32 s86, s63, 0
	s_mov_b32 s87, -2
	ds_read_b128 v[152:155], v148
	ds_read_b128 v[156:159], v148 offset:1024
	ds_read_b128 v[160:163], v148 offset:2048
	ds_read_b128 v[164:167], v148 offset:3072
	ds_read_b128 v[168:171], v149
	ds_read_b128 v[172:175], v149 offset:1024
	ds_read_b128 v[176:179], v149 offset:2048
	ds_read_b128 v[184:187], v149 offset:3072
	s_add_u32 s62, s60, 0xfffc0080
	s_addc_u32 s63, s61, -1
	s_cmp_eq_u32 s87, 12
	s_cselect_b32 s65, s53, s63
	s_cselect_b32 s64, s83, s62
	s_cselect_b32 s63, s49, s86
	s_cselect_b32 s62, s84, s85
	v_lshl_add_u64 v[220:221], s[60:61], 0, v[138:139]
	s_add_i32 m0, s69, 0xc000
	ds_read_b128 v[188:191], v150
	ds_read_b128 v[192:195], v150 offset:1024
	ds_read_b128 v[196:199], v150 offset:2048
	ds_read_b128 v[200:203], v150 offset:3072
	ds_read_b128 v[204:207], v150 offset:4096
	ds_read_b128 v[208:211], v150 offset:5120
	ds_read_b128 v[212:215], v150 offset:6144
	ds_read_b128 v[216:219], v150 offset:7168
	global_load_lds_dwordx4 v[220:221], off
	v_lshl_add_u64 v[220:221], s[60:61], 0, v[140:141]
	s_add_i32 m0, s69, 0xe000
	s_nop 0
	global_load_lds_dwordx4 v[220:221], off
	s_waitcnt vmcnt(8)
	s_waitcnt lgkmcnt(0)
	s_barrier
	s_setprio 1
	s_waitcnt lgkmcnt(0)
	v_mfma_f32_16x16x32_bf16 v[124:127], v[152:155], v[188:191], 0
	v_mfma_f32_16x16x32_bf16 v[124:127], v[156:159], v[192:195], v[124:127]
	v_mfma_f32_16x16x32_bf16 v[120:123], v[160:163], v[188:191], 0
	v_mfma_f32_16x16x32_bf16 v[120:123], v[164:167], v[192:195], v[120:123]
	v_mfma_f32_16x16x32_bf16 v[116:119], v[152:155], v[196:199], 0
	v_mfma_f32_16x16x32_bf16 v[116:119], v[156:159], v[200:203], v[116:119]
	v_mfma_f32_16x16x32_bf16 v[112:115], v[160:163], v[196:199], 0
	v_mfma_f32_16x16x32_bf16 v[112:115], v[164:167], v[200:203], v[112:115]
	v_mfma_f32_16x16x32_bf16 v[108:111], v[152:155], v[204:207], 0
	v_mfma_f32_16x16x32_bf16 v[108:111], v[156:159], v[208:211], v[108:111]
	v_mfma_f32_16x16x32_bf16 v[104:107], v[160:163], v[204:207], 0
	v_mfma_f32_16x16x32_bf16 v[104:107], v[164:167], v[208:211], v[104:107]
	v_mfma_f32_16x16x32_bf16 v[100:103], v[152:155], v[212:215], 0
	v_mfma_f32_16x16x32_bf16 v[100:103], v[156:159], v[216:219], v[100:103]
	v_mfma_f32_16x16x32_bf16 v[96:99], v[160:163], v[212:215], 0
	v_mfma_f32_16x16x32_bf16 v[96:99], v[164:167], v[216:219], v[96:99]
	v_mfma_f32_16x16x32_bf16 v[68:71], v[168:171], v[188:191], 0
	v_mfma_f32_16x16x32_bf16 v[68:71], v[172:175], v[192:195], v[68:71]
	v_mfma_f32_16x16x32_bf16 v[64:67], v[176:179], v[188:191], 0
	v_mfma_f32_16x16x32_bf16 v[64:67], v[184:187], v[192:195], v[64:67]
	v_mfma_f32_16x16x32_bf16 v[52:55], v[168:171], v[196:199], 0
	v_mfma_f32_16x16x32_bf16 v[52:55], v[172:175], v[200:203], v[52:55]
	v_mfma_f32_16x16x32_bf16 v[48:51], v[176:179], v[196:199], 0
	v_mfma_f32_16x16x32_bf16 v[48:51], v[184:187], v[200:203], v[48:51]
	v_mfma_f32_16x16x32_bf16 v[44:47], v[168:171], v[204:207], 0
	v_mfma_f32_16x16x32_bf16 v[44:47], v[172:175], v[208:211], v[44:47]
	v_mfma_f32_16x16x32_bf16 v[40:43], v[176:179], v[204:207], 0
	v_mfma_f32_16x16x32_bf16 v[40:43], v[184:187], v[208:211], v[40:43]
	v_mfma_f32_16x16x32_bf16 v[36:39], v[168:171], v[212:215], 0
	v_mfma_f32_16x16x32_bf16 v[36:39], v[172:175], v[216:219], v[36:39]
	v_mfma_f32_16x16x32_bf16 v[32:35], v[176:179], v[212:215], 0
	v_mfma_f32_16x16x32_bf16 v[32:35], v[184:187], v[216:219], v[32:35]
	s_setprio 0
	s_barrier
	s_add_i32 s79, s77, s68
	v_lshl_add_u64 v[220:221], s[62:63], 0, v[130:131]
	s_mov_b32 m0, s79
	ds_read_b128 v[188:191], v150 offset:16384
	ds_read_b128 v[192:195], v150 offset:17408
	ds_read_b128 v[196:199], v150 offset:18432
	ds_read_b128 v[200:203], v150 offset:19456
	ds_read_b128 v[204:207], v150 offset:20480
	ds_read_b128 v[208:211], v150 offset:21504
	ds_read_b128 v[212:215], v150 offset:22528
	ds_read_b128 v[216:219], v150 offset:23552
	global_load_lds_dwordx4 v[220:221], off
	s_add_i32 m0, s79, 0x2000
	s_add_u32 s88, s62, 0x40000
	v_lshl_add_u64 v[222:223], s[62:63], 0, v[134:135]
	s_addc_u32 s89, s63, 0
	s_add_i32 s79, s82, s68
	global_load_lds_dwordx4 v[222:223], off
	v_lshl_add_u64 v[224:225], s[88:89], 0, v[130:131]
	s_mov_b32 m0, s79
	v_lshl_add_u64 v[226:227], s[64:65], 0, v[132:133]
	global_load_lds_dwordx4 v[224:225], off
	v_lshl_add_u64 v[224:225], s[88:89], 0, v[134:135]
	s_add_i32 m0, s79, 0x2000
	s_nop 0
	global_load_lds_dwordx4 v[224:225], off
	v_lshl_add_u64 v[224:225], s[64:65], 0, v[128:129]
	s_mov_b32 m0, s69
	s_nop 0
	global_load_lds_dwordx4 v[224:225], off
	s_mov_b32 m0, s70
	s_nop 0
	global_load_lds_dwordx4 v[226:227], off
	s_waitcnt vmcnt(8)
	s_waitcnt lgkmcnt(0)
	s_barrier
	s_setprio 1
	s_waitcnt lgkmcnt(0)
	v_mfma_f32_16x16x32_bf16 v[92:95], v[152:155], v[188:191], 0
	v_mfma_f32_16x16x32_bf16 v[92:95], v[156:159], v[192:195], v[92:95]
	v_mfma_f32_16x16x32_bf16 v[88:91], v[160:163], v[188:191], 0
	v_mfma_f32_16x16x32_bf16 v[88:91], v[164:167], v[192:195], v[88:91]
	v_mfma_f32_16x16x32_bf16 v[84:87], v[152:155], v[196:199], 0
	v_mfma_f32_16x16x32_bf16 v[84:87], v[156:159], v[200:203], v[84:87]
	v_mfma_f32_16x16x32_bf16 v[80:83], v[160:163], v[196:199], 0
	v_mfma_f32_16x16x32_bf16 v[80:83], v[164:167], v[200:203], v[80:83]
	v_mfma_f32_16x16x32_bf16 v[76:79], v[152:155], v[204:207], 0
	v_mfma_f32_16x16x32_bf16 v[76:79], v[156:159], v[208:211], v[76:79]
	v_mfma_f32_16x16x32_bf16 v[72:75], v[160:163], v[204:207], 0
	v_mfma_f32_16x16x32_bf16 v[72:75], v[164:167], v[208:211], v[72:75]
	v_mfma_f32_16x16x32_bf16 v[60:63], v[152:155], v[212:215], 0
	v_mfma_f32_16x16x32_bf16 v[60:63], v[156:159], v[216:219], v[60:63]
	v_mfma_f32_16x16x32_bf16 v[56:59], v[160:163], v[212:215], 0
	v_mfma_f32_16x16x32_bf16 v[56:59], v[164:167], v[216:219], v[56:59]
	v_mfma_f32_16x16x32_bf16 v[28:31], v[168:171], v[188:191], 0
	v_mfma_f32_16x16x32_bf16 v[28:31], v[172:175], v[192:195], v[28:31]
	v_mfma_f32_16x16x32_bf16 v[24:27], v[176:179], v[188:191], 0
	v_mfma_f32_16x16x32_bf16 v[24:27], v[184:187], v[192:195], v[24:27]
	v_mfma_f32_16x16x32_bf16 v[20:23], v[168:171], v[196:199], 0
	v_mfma_f32_16x16x32_bf16 v[20:23], v[172:175], v[200:203], v[20:23]
	v_mfma_f32_16x16x32_bf16 v[16:19], v[176:179], v[196:199], 0
	v_mfma_f32_16x16x32_bf16 v[16:19], v[184:187], v[200:203], v[16:19]
	v_mfma_f32_16x16x32_bf16 v[12:15], v[168:171], v[204:207], 0
	v_mfma_f32_16x16x32_bf16 v[12:15], v[172:175], v[208:211], v[12:15]
	v_mfma_f32_16x16x32_bf16 v[8:11], v[176:179], v[204:207], 0
	v_mfma_f32_16x16x32_bf16 v[8:11], v[184:187], v[208:211], v[8:11]
	v_mfma_f32_16x16x32_bf16 v[4:7], v[168:171], v[212:215], 0
	v_mfma_f32_16x16x32_bf16 v[4:7], v[172:175], v[216:219], v[4:7]
	v_mfma_f32_16x16x32_bf16 v[0:3], v[176:179], v[212:215], 0
	v_mfma_f32_16x16x32_bf16 v[0:3], v[184:187], v[216:219], v[0:3]
	s_setprio 0
	s_barrier
	s_branch .Lmid_gemm9
	.p2align	6

.LBB0_1310:
	s_ashr_i32 s49, s48, 31
	s_lshl_b64 s[50:51], s[48:49], 19
	s_add_u32 s50, s38, s50
	s_addc_u32 s51, s39, s51
	s_and_b64 s[52:53], s[10:11], exec
	s_cselect_b32 s49, s51, s57
	s_cselect_b32 s82, s50, s56
	s_ashr_i32 s47, s46, 31
	s_lshl_b64 s[52:53], s[46:47], 19
	s_add_u32 s52, s62, s52
	s_addc_u32 s53, s63, s53
	s_and_b64 s[60:61], s[10:11], exec
	s_cselect_b32 s47, s53, s59
	s_cselect_b32 s83, s52, s58
	s_add_u32 s56, s56, 0x40080
	s_addc_u32 s57, s57, 0
	s_add_u32 s84, s58, 0x100
	s_addc_u32 s85, s59, 0
	s_mov_b32 s86, -2
	ds_read_b128 v[152:155], v149
	ds_read_b128 v[156:159], v149 offset:1024
	ds_read_b128 v[160:163], v149 offset:2048
	ds_read_b128 v[164:167], v149 offset:3072
	ds_read_b128 v[168:171], v150
	ds_read_b128 v[172:175], v150 offset:1024
	ds_read_b128 v[176:179], v150 offset:2048
	ds_read_b128 v[184:187], v150 offset:3072
	s_add_u32 s58, s56, 0xfffc0080
	s_addc_u32 s59, s57, -1
	s_cmp_eq_u32 s86, 12
	s_cselect_b32 s61, s49, s59
	s_cselect_b32 s60, s82, s58
	s_cselect_b32 s59, s47, s85
	s_cselect_b32 s58, s83, s84
	v_lshl_add_u64 v[144:145], s[56:57], 0, v[136:137]
	s_add_i32 m0, s55, 0xc000
	ds_read_b128 v[188:191], v151
	ds_read_b128 v[192:195], v151 offset:1024
	ds_read_b128 v[196:199], v151 offset:2048
	ds_read_b128 v[200:203], v151 offset:3072
	ds_read_b128 v[204:207], v151 offset:4096
	ds_read_b128 v[208:211], v151 offset:5120
	ds_read_b128 v[212:215], v151 offset:6144
	ds_read_b128 v[216:219], v151 offset:7168
	global_load_lds_dwordx4 v[144:145], off
	v_lshl_add_u64 v[144:145], s[56:57], 0, v[138:139]
	s_add_i32 m0, s55, 0xe000
	s_nop 0
	global_load_lds_dwordx4 v[144:145], off
	s_waitcnt vmcnt(8)
	s_waitcnt lgkmcnt(0)
	s_barrier
	s_setprio 1
	s_waitcnt lgkmcnt(0)
	v_mfma_f32_16x16x32_bf16 v[124:127], v[152:155], v[188:191], 0
	v_mfma_f32_16x16x32_bf16 v[124:127], v[156:159], v[192:195], v[124:127]
	v_mfma_f32_16x16x32_bf16 v[120:123], v[160:163], v[188:191], 0
	v_mfma_f32_16x16x32_bf16 v[120:123], v[164:167], v[192:195], v[120:123]
	v_mfma_f32_16x16x32_bf16 v[116:119], v[152:155], v[196:199], 0
	v_mfma_f32_16x16x32_bf16 v[116:119], v[156:159], v[200:203], v[116:119]
	v_mfma_f32_16x16x32_bf16 v[108:111], v[160:163], v[196:199], 0
	v_mfma_f32_16x16x32_bf16 v[108:111], v[164:167], v[200:203], v[108:111]
	v_mfma_f32_16x16x32_bf16 v[100:103], v[152:155], v[204:207], 0
	v_mfma_f32_16x16x32_bf16 v[100:103], v[156:159], v[208:211], v[100:103]
	v_mfma_f32_16x16x32_bf16 v[92:95], v[160:163], v[204:207], 0
	v_mfma_f32_16x16x32_bf16 v[92:95], v[164:167], v[208:211], v[92:95]
	v_mfma_f32_16x16x32_bf16 v[84:87], v[152:155], v[212:215], 0
	v_mfma_f32_16x16x32_bf16 v[84:87], v[156:159], v[216:219], v[84:87]
	v_mfma_f32_16x16x32_bf16 v[76:79], v[160:163], v[212:215], 0
	v_mfma_f32_16x16x32_bf16 v[76:79], v[164:167], v[216:219], v[76:79]
	v_mfma_f32_16x16x32_bf16 v[112:115], v[168:171], v[188:191], 0
	v_mfma_f32_16x16x32_bf16 v[112:115], v[172:175], v[192:195], v[112:115]
	v_mfma_f32_16x16x32_bf16 v[104:107], v[176:179], v[188:191], 0
	v_mfma_f32_16x16x32_bf16 v[104:107], v[184:187], v[192:195], v[104:107]
	v_mfma_f32_16x16x32_bf16 v[96:99], v[168:171], v[196:199], 0
	v_mfma_f32_16x16x32_bf16 v[96:99], v[172:175], v[200:203], v[96:99]
	v_mfma_f32_16x16x32_bf16 v[88:91], v[176:179], v[196:199], 0
	v_mfma_f32_16x16x32_bf16 v[88:91], v[184:187], v[200:203], v[88:91]
	v_mfma_f32_16x16x32_bf16 v[80:83], v[168:171], v[204:207], 0
	v_mfma_f32_16x16x32_bf16 v[80:83], v[172:175], v[208:211], v[80:83]
	v_mfma_f32_16x16x32_bf16 v[72:75], v[176:179], v[204:207], 0
	v_mfma_f32_16x16x32_bf16 v[72:75], v[184:187], v[208:211], v[72:75]
	v_mfma_f32_16x16x32_bf16 v[68:71], v[168:171], v[212:215], 0
	v_mfma_f32_16x16x32_bf16 v[68:71], v[172:175], v[216:219], v[68:71]
	v_mfma_f32_16x16x32_bf16 v[64:67], v[176:179], v[212:215], 0
	v_mfma_f32_16x16x32_bf16 v[64:67], v[184:187], v[216:219], v[64:67]
	s_setprio 0
	s_barrier
	s_add_i32 s79, s71, s64
	v_lshl_add_u64 v[144:145], s[58:59], 0, v[130:131]
	s_mov_b32 m0, s79
	ds_read_b128 v[188:191], v151 offset:16384
	ds_read_b128 v[192:195], v151 offset:17408
	ds_read_b128 v[196:199], v151 offset:18432
	ds_read_b128 v[200:203], v151 offset:19456
	ds_read_b128 v[204:207], v151 offset:20480
	ds_read_b128 v[208:211], v151 offset:21504
	ds_read_b128 v[212:215], v151 offset:22528
	ds_read_b128 v[216:219], v151 offset:23552
	global_load_lds_dwordx4 v[144:145], off
	s_add_i32 m0, s79, 0x2000
	s_add_u32 s88, s58, 0x40000
	v_lshl_add_u64 v[220:221], s[58:59], 0, v[134:135]
	s_addc_u32 s89, s59, 0
	s_add_i32 s79, s72, s64
	global_load_lds_dwordx4 v[220:221], off
	v_lshl_add_u64 v[222:223], s[88:89], 0, v[130:131]
	s_mov_b32 m0, s79
	v_lshl_add_u64 v[224:225], s[60:61], 0, v[132:133]
	global_load_lds_dwordx4 v[222:223], off
	v_lshl_add_u64 v[222:223], s[88:89], 0, v[134:135]
	s_add_i32 m0, s79, 0x2000
	s_nop 0
	global_load_lds_dwordx4 v[222:223], off
	v_lshl_add_u64 v[222:223], s[60:61], 0, v[128:129]
	s_mov_b32 m0, s55
	s_nop 0
	global_load_lds_dwordx4 v[222:223], off
	s_mov_b32 m0, s65
	s_nop 0
	global_load_lds_dwordx4 v[224:225], off
	s_waitcnt vmcnt(8)
	s_waitcnt lgkmcnt(0)
	s_barrier
	s_setprio 1
	s_waitcnt lgkmcnt(0)
	v_mfma_f32_16x16x32_bf16 v[60:63], v[152:155], v[188:191], 0
	v_mfma_f32_16x16x32_bf16 v[60:63], v[156:159], v[192:195], v[60:63]
	v_mfma_f32_16x16x32_bf16 v[56:59], v[160:163], v[188:191], 0
	v_mfma_f32_16x16x32_bf16 v[56:59], v[164:167], v[192:195], v[56:59]
	v_mfma_f32_16x16x32_bf16 v[52:55], v[152:155], v[196:199], 0
	v_mfma_f32_16x16x32_bf16 v[52:55], v[156:159], v[200:203], v[52:55]
	v_mfma_f32_16x16x32_bf16 v[44:47], v[160:163], v[196:199], 0
	v_mfma_f32_16x16x32_bf16 v[44:47], v[164:167], v[200:203], v[44:47]
	v_mfma_f32_16x16x32_bf16 v[36:39], v[152:155], v[204:207], 0
	v_mfma_f32_16x16x32_bf16 v[36:39], v[156:159], v[208:211], v[36:39]
	v_mfma_f32_16x16x32_bf16 v[28:31], v[160:163], v[204:207], 0
	v_mfma_f32_16x16x32_bf16 v[28:31], v[164:167], v[208:211], v[28:31]
	v_mfma_f32_16x16x32_bf16 v[20:23], v[152:155], v[212:215], 0
	v_mfma_f32_16x16x32_bf16 v[20:23], v[156:159], v[216:219], v[20:23]
	v_mfma_f32_16x16x32_bf16 v[12:15], v[160:163], v[212:215], 0
	v_mfma_f32_16x16x32_bf16 v[12:15], v[164:167], v[216:219], v[12:15]
	v_mfma_f32_16x16x32_bf16 v[48:51], v[168:171], v[188:191], 0
	v_mfma_f32_16x16x32_bf16 v[48:51], v[172:175], v[192:195], v[48:51]
	v_mfma_f32_16x16x32_bf16 v[40:43], v[176:179], v[188:191], 0
	v_mfma_f32_16x16x32_bf16 v[40:43], v[184:187], v[192:195], v[40:43]
	v_mfma_f32_16x16x32_bf16 v[32:35], v[168:171], v[196:199], 0
	v_mfma_f32_16x16x32_bf16 v[32:35], v[172:175], v[200:203], v[32:35]
	v_mfma_f32_16x16x32_bf16 v[24:27], v[176:179], v[196:199], 0
	v_mfma_f32_16x16x32_bf16 v[24:27], v[184:187], v[200:203], v[24:27]
	v_mfma_f32_16x16x32_bf16 v[16:19], v[168:171], v[204:207], 0
	v_mfma_f32_16x16x32_bf16 v[16:19], v[172:175], v[208:211], v[16:19]
	v_mfma_f32_16x16x32_bf16 v[8:11], v[176:179], v[204:207], 0
	v_mfma_f32_16x16x32_bf16 v[8:11], v[184:187], v[208:211], v[8:11]
	v_mfma_f32_16x16x32_bf16 v[4:7], v[168:171], v[212:215], 0
	v_mfma_f32_16x16x32_bf16 v[4:7], v[172:175], v[216:219], v[4:7]
	v_mfma_f32_16x16x32_bf16 v[0:3], v[176:179], v[212:215], 0
	v_mfma_f32_16x16x32_bf16 v[0:3], v[184:187], v[216:219], v[0:3]
	s_setprio 0
	s_barrier
	s_branch .Lmid_gemm10
	.p2align	6

.LBB0_1433:
	s_ashr_i32 s19, s18, 31
	s_lshl_b64 s[30:31], s[18:19], 19
	s_add_u32 s30, s80, s30
	s_addc_u32 s31, s81, s31
	s_and_b64 s[36:37], s[8:9], exec
	s_cselect_b32 s19, s31, s47
	s_cselect_b32 s66, s30, s46
	s_ashr_i32 s17, s16, 31
	s_lshl_b64 s[36:37], s[16:17], 19
	s_add_u32 s36, s52, s36
	s_addc_u32 s37, s53, s37
	s_and_b64 s[50:51], s[8:9], exec
	s_cselect_b32 s17, s37, s49
	s_cselect_b32 s67, s36, s48
	s_add_u32 s46, s46, 0x40080
	s_addc_u32 s47, s47, 0
	s_add_u32 s68, s48, 0x100
	s_addc_u32 s69, s49, 0
	s_mov_b32 s70, -2
	ds_read_b128 v[140:143], v147
	ds_read_b128 v[150:153], v147 offset:1024
	ds_read_b128 v[154:157], v147 offset:2048
	ds_read_b128 v[158:161], v147 offset:3072
	ds_read_b128 v[162:165], v148
	ds_read_b128 v[166:169], v148 offset:1024
	ds_read_b128 v[170:173], v148 offset:2048
	ds_read_b128 v[174:177], v148 offset:3072
	s_add_u32 s48, s46, 0xfffc0080
	s_addc_u32 s49, s47, -1
	s_cmp_eq_u32 s70, 12
	s_cselect_b32 s51, s19, s49
	s_cselect_b32 s50, s66, s48
	s_cselect_b32 s49, s17, s69
	s_cselect_b32 s48, s67, s68
	v_lshl_add_u64 v[178:179], s[46:47], 0, v[132:133]
	s_add_i32 m0, s45, 0xc000
	ds_read_b128 v[184:187], v149
	ds_read_b128 v[188:191], v149 offset:1024
	ds_read_b128 v[192:195], v149 offset:2048
	ds_read_b128 v[196:199], v149 offset:3072
	ds_read_b128 v[200:203], v149 offset:4096
	ds_read_b128 v[204:207], v149 offset:5120
	ds_read_b128 v[208:211], v149 offset:6144
	ds_read_b128 v[212:215], v149 offset:7168
	global_load_lds_dwordx4 v[178:179], off
	v_lshl_add_u64 v[178:179], s[46:47], 0, v[134:135]
	s_add_i32 m0, s45, 0xe000
	s_nop 0
	global_load_lds_dwordx4 v[178:179], off
	s_waitcnt vmcnt(8)
	s_waitcnt lgkmcnt(0)
	s_barrier
	s_setprio 1
	s_waitcnt lgkmcnt(0)
	v_mfma_f32_16x16x32_bf16 v[124:127], v[140:143], v[184:187], 0
	v_mfma_f32_16x16x32_bf16 v[124:127], v[150:153], v[188:191], v[124:127]
	v_mfma_f32_16x16x32_bf16 v[120:123], v[154:157], v[184:187], 0
	v_mfma_f32_16x16x32_bf16 v[120:123], v[158:161], v[188:191], v[120:123]
	v_mfma_f32_16x16x32_bf16 v[108:111], v[140:143], v[192:195], 0
	v_mfma_f32_16x16x32_bf16 v[108:111], v[150:153], v[196:199], v[108:111]
	v_mfma_f32_16x16x32_bf16 v[104:107], v[154:157], v[192:195], 0
	v_mfma_f32_16x16x32_bf16 v[104:107], v[158:161], v[196:199], v[104:107]
	v_mfma_f32_16x16x32_bf16 v[92:95], v[140:143], v[200:203], 0
	v_mfma_f32_16x16x32_bf16 v[92:95], v[150:153], v[204:207], v[92:95]
	v_mfma_f32_16x16x32_bf16 v[88:91], v[154:157], v[200:203], 0
	v_mfma_f32_16x16x32_bf16 v[88:91], v[158:161], v[204:207], v[88:91]
	v_mfma_f32_16x16x32_bf16 v[76:79], v[140:143], v[208:211], 0
	v_mfma_f32_16x16x32_bf16 v[76:79], v[150:153], v[212:215], v[76:79]
	v_mfma_f32_16x16x32_bf16 v[72:75], v[154:157], v[208:211], 0
	v_mfma_f32_16x16x32_bf16 v[72:75], v[158:161], v[212:215], v[72:75]
	v_mfma_f32_16x16x32_bf16 v[116:119], v[162:165], v[184:187], 0
	v_mfma_f32_16x16x32_bf16 v[116:119], v[166:169], v[188:191], v[116:119]
	v_mfma_f32_16x16x32_bf16 v[112:115], v[170:173], v[184:187], 0
	v_mfma_f32_16x16x32_bf16 v[112:115], v[174:177], v[188:191], v[112:115]
	v_mfma_f32_16x16x32_bf16 v[100:103], v[162:165], v[192:195], 0
	v_mfma_f32_16x16x32_bf16 v[100:103], v[166:169], v[196:199], v[100:103]
	v_mfma_f32_16x16x32_bf16 v[96:99], v[170:173], v[192:195], 0
	v_mfma_f32_16x16x32_bf16 v[96:99], v[174:177], v[196:199], v[96:99]
	v_mfma_f32_16x16x32_bf16 v[84:87], v[162:165], v[200:203], 0
	v_mfma_f32_16x16x32_bf16 v[84:87], v[166:169], v[204:207], v[84:87]
	v_mfma_f32_16x16x32_bf16 v[80:83], v[170:173], v[200:203], 0
	v_mfma_f32_16x16x32_bf16 v[80:83], v[174:177], v[204:207], v[80:83]
	v_mfma_f32_16x16x32_bf16 v[68:71], v[162:165], v[208:211], 0
	v_mfma_f32_16x16x32_bf16 v[68:71], v[166:169], v[212:215], v[68:71]
	v_mfma_f32_16x16x32_bf16 v[64:67], v[170:173], v[208:211], 0
	v_mfma_f32_16x16x32_bf16 v[64:67], v[174:177], v[212:215], v[64:67]
	s_setprio 0
	s_barrier
	s_add_i32 s71, s62, s54
	v_lshl_add_u64 v[178:179], s[48:49], 0, v[130:131]
	s_mov_b32 m0, s71
	ds_read_b128 v[184:187], v149 offset:16384
	ds_read_b128 v[188:191], v149 offset:17408
	ds_read_b128 v[192:195], v149 offset:18432
	ds_read_b128 v[196:199], v149 offset:19456
	ds_read_b128 v[200:203], v149 offset:20480
	ds_read_b128 v[204:207], v149 offset:21504
	ds_read_b128 v[208:211], v149 offset:22528
	ds_read_b128 v[212:215], v149 offset:23552
	global_load_lds_dwordx4 v[178:179], off
	s_add_i32 m0, s71, 0x2000
	s_add_u32 s72, s48, 0x40000
	v_lshl_add_u64 v[216:217], s[48:49], 0, v[128:129]
	s_addc_u32 s73, s49, 0
	s_add_i32 s71, s63, s54
	global_load_lds_dwordx4 v[216:217], off
	v_lshl_add_u64 v[218:219], s[72:73], 0, v[130:131]
	s_mov_b32 m0, s71
	v_lshl_add_u64 v[220:221], s[50:51], 0, v[128:129]
	global_load_lds_dwordx4 v[218:219], off
	v_lshl_add_u64 v[218:219], s[72:73], 0, v[128:129]
	s_add_i32 m0, s71, 0x2000
	s_nop 0
	global_load_lds_dwordx4 v[218:219], off
	v_lshl_add_u64 v[218:219], s[50:51], 0, v[130:131]
	s_mov_b32 m0, s45
	s_nop 0
	global_load_lds_dwordx4 v[218:219], off
	s_mov_b32 m0, s56
	s_nop 0
	global_load_lds_dwordx4 v[220:221], off
	s_waitcnt vmcnt(8)
	s_waitcnt lgkmcnt(0)
	s_barrier
	s_setprio 1
	s_waitcnt lgkmcnt(0)
	v_mfma_f32_16x16x32_bf16 v[60:63], v[140:143], v[184:187], 0
	v_mfma_f32_16x16x32_bf16 v[60:63], v[150:153], v[188:191], v[60:63]
	v_mfma_f32_16x16x32_bf16 v[56:59], v[154:157], v[184:187], 0
	v_mfma_f32_16x16x32_bf16 v[56:59], v[158:161], v[188:191], v[56:59]
	v_mfma_f32_16x16x32_bf16 v[44:47], v[140:143], v[192:195], 0
	v_mfma_f32_16x16x32_bf16 v[44:47], v[150:153], v[196:199], v[44:47]
	v_mfma_f32_16x16x32_bf16 v[40:43], v[154:157], v[192:195], 0
	v_mfma_f32_16x16x32_bf16 v[40:43], v[158:161], v[196:199], v[40:43]
	v_mfma_f32_16x16x32_bf16 v[28:31], v[140:143], v[200:203], 0
	v_mfma_f32_16x16x32_bf16 v[28:31], v[150:153], v[204:207], v[28:31]
	v_mfma_f32_16x16x32_bf16 v[24:27], v[154:157], v[200:203], 0
	v_mfma_f32_16x16x32_bf16 v[24:27], v[158:161], v[204:207], v[24:27]
	v_mfma_f32_16x16x32_bf16 v[12:15], v[140:143], v[208:211], 0
	v_mfma_f32_16x16x32_bf16 v[12:15], v[150:153], v[212:215], v[12:15]
	v_mfma_f32_16x16x32_bf16 v[8:11], v[154:157], v[208:211], 0
	v_mfma_f32_16x16x32_bf16 v[8:11], v[158:161], v[212:215], v[8:11]
	v_mfma_f32_16x16x32_bf16 v[52:55], v[162:165], v[184:187], 0
	v_mfma_f32_16x16x32_bf16 v[52:55], v[166:169], v[188:191], v[52:55]
	v_mfma_f32_16x16x32_bf16 v[48:51], v[170:173], v[184:187], 0
	v_mfma_f32_16x16x32_bf16 v[48:51], v[174:177], v[188:191], v[48:51]
	v_mfma_f32_16x16x32_bf16 v[36:39], v[162:165], v[192:195], 0
	v_mfma_f32_16x16x32_bf16 v[36:39], v[166:169], v[196:199], v[36:39]
	v_mfma_f32_16x16x32_bf16 v[32:35], v[170:173], v[192:195], 0
	v_mfma_f32_16x16x32_bf16 v[32:35], v[174:177], v[196:199], v[32:35]
	v_mfma_f32_16x16x32_bf16 v[20:23], v[162:165], v[200:203], 0
	v_mfma_f32_16x16x32_bf16 v[20:23], v[166:169], v[204:207], v[20:23]
	v_mfma_f32_16x16x32_bf16 v[16:19], v[170:173], v[200:203], 0
	v_mfma_f32_16x16x32_bf16 v[16:19], v[174:177], v[204:207], v[16:19]
	v_mfma_f32_16x16x32_bf16 v[4:7], v[162:165], v[208:211], 0
	v_mfma_f32_16x16x32_bf16 v[4:7], v[166:169], v[212:215], v[4:7]
	v_mfma_f32_16x16x32_bf16 v[0:3], v[170:173], v[208:211], 0
	v_mfma_f32_16x16x32_bf16 v[0:3], v[174:177], v[212:215], v[0:3]
	s_setprio 0
	s_barrier
	s_branch .Lmid_gemm11
	.p2align	6

.LBB0_1513:
	s_add_u32 s74, s48, 0x100
	s_addc_u32 s75, s49, 0
	s_mov_b32 s76, -2
	ds_read_b128 v[152:155], v149
	ds_read_b128 v[156:159], v149 offset:1024
	ds_read_b128 v[160:163], v149 offset:2048
	ds_read_b128 v[164:167], v149 offset:3072
	ds_read_b128 v[168:171], v150
	ds_read_b128 v[172:175], v150 offset:1024
	ds_read_b128 v[176:179], v150 offset:2048
	ds_read_b128 v[184:187], v150 offset:3072
	s_add_u32 s48, s46, 0x100
	s_addc_u32 s49, s47, 0
	s_cmp_eq_u32 s76, 40
	s_cselect_b32 s53, s9, s49
	s_cselect_b32 s52, s8, s48
	s_cselect_b32 s51, s45, s75
	s_cselect_b32 s50, s44, s74
	v_lshl_add_u64 v[144:145], s[46:47], 0, v[136:137]
	s_add_i32 m0, s57, 0xc000
	ds_read_b128 v[188:191], v151
	ds_read_b128 v[192:195], v151 offset:1024
	ds_read_b128 v[196:199], v151 offset:2048
	ds_read_b128 v[200:203], v151 offset:3072
	ds_read_b128 v[204:207], v151 offset:4096
	ds_read_b128 v[208:211], v151 offset:5120
	ds_read_b128 v[212:215], v151 offset:6144
	ds_read_b128 v[216:219], v151 offset:7168
	global_load_lds_dwordx4 v[144:145], off
	v_lshl_add_u64 v[144:145], s[46:47], 0, v[138:139]
	s_add_i32 m0, s57, 0xe000
	s_nop 0
	global_load_lds_dwordx4 v[144:145], off
	s_waitcnt vmcnt(8)
	s_waitcnt lgkmcnt(0)
	s_barrier
	s_setprio 1
	s_waitcnt lgkmcnt(0)
	v_mfma_f32_16x16x32_bf16 v[124:127], v[152:155], v[188:191], 0
	v_mfma_f32_16x16x32_bf16 v[124:127], v[156:159], v[192:195], v[124:127]
	v_mfma_f32_16x16x32_bf16 v[120:123], v[160:163], v[188:191], 0
	v_mfma_f32_16x16x32_bf16 v[120:123], v[164:167], v[192:195], v[120:123]
	v_mfma_f32_16x16x32_bf16 v[116:119], v[152:155], v[196:199], 0
	v_mfma_f32_16x16x32_bf16 v[116:119], v[156:159], v[200:203], v[116:119]
	v_mfma_f32_16x16x32_bf16 v[108:111], v[160:163], v[196:199], 0
	v_mfma_f32_16x16x32_bf16 v[108:111], v[164:167], v[200:203], v[108:111]
	v_mfma_f32_16x16x32_bf16 v[100:103], v[152:155], v[204:207], 0
	v_mfma_f32_16x16x32_bf16 v[100:103], v[156:159], v[208:211], v[100:103]
	v_mfma_f32_16x16x32_bf16 v[92:95], v[160:163], v[204:207], 0
	v_mfma_f32_16x16x32_bf16 v[92:95], v[164:167], v[208:211], v[92:95]
	v_mfma_f32_16x16x32_bf16 v[84:87], v[152:155], v[212:215], 0
	v_mfma_f32_16x16x32_bf16 v[84:87], v[156:159], v[216:219], v[84:87]
	v_mfma_f32_16x16x32_bf16 v[76:79], v[160:163], v[212:215], 0
	v_mfma_f32_16x16x32_bf16 v[76:79], v[164:167], v[216:219], v[76:79]
	v_mfma_f32_16x16x32_bf16 v[112:115], v[168:171], v[188:191], 0
	v_mfma_f32_16x16x32_bf16 v[112:115], v[172:175], v[192:195], v[112:115]
	v_mfma_f32_16x16x32_bf16 v[104:107], v[176:179], v[188:191], 0
	v_mfma_f32_16x16x32_bf16 v[104:107], v[184:187], v[192:195], v[104:107]
	v_mfma_f32_16x16x32_bf16 v[96:99], v[168:171], v[196:199], 0
	v_mfma_f32_16x16x32_bf16 v[96:99], v[172:175], v[200:203], v[96:99]
	v_mfma_f32_16x16x32_bf16 v[88:91], v[176:179], v[196:199], 0
	v_mfma_f32_16x16x32_bf16 v[88:91], v[184:187], v[200:203], v[88:91]
	v_mfma_f32_16x16x32_bf16 v[80:83], v[168:171], v[204:207], 0
	v_mfma_f32_16x16x32_bf16 v[80:83], v[172:175], v[208:211], v[80:83]
	v_mfma_f32_16x16x32_bf16 v[72:75], v[176:179], v[204:207], 0
	v_mfma_f32_16x16x32_bf16 v[72:75], v[184:187], v[208:211], v[72:75]
	v_mfma_f32_16x16x32_bf16 v[68:71], v[168:171], v[212:215], 0
	v_mfma_f32_16x16x32_bf16 v[68:71], v[172:175], v[216:219], v[68:71]
	v_mfma_f32_16x16x32_bf16 v[64:67], v[176:179], v[212:215], 0
	v_mfma_f32_16x16x32_bf16 v[64:67], v[184:187], v[216:219], v[64:67]
	s_setprio 0
	s_barrier
	s_add_i32 s46, s64, s56
	v_lshl_add_u64 v[144:145], s[50:51], 0, v[130:131]
	s_mov_b32 m0, s46
	ds_read_b128 v[188:191], v151 offset:16384
	ds_read_b128 v[192:195], v151 offset:17408
	ds_read_b128 v[196:199], v151 offset:18432
	ds_read_b128 v[200:203], v151 offset:19456
	ds_read_b128 v[204:207], v151 offset:20480
	ds_read_b128 v[208:211], v151 offset:21504
	ds_read_b128 v[212:215], v151 offset:22528
	ds_read_b128 v[216:219], v151 offset:23552
	global_load_lds_dwordx4 v[144:145], off
	s_add_i32 m0, s46, 0x2000
	s_add_u32 s46, s50, 0xb0000
	v_lshl_add_u64 v[220:221], s[50:51], 0, v[134:135]
	s_addc_u32 s47, s51, 0
	s_add_i32 s77, s65, s56
	global_load_lds_dwordx4 v[220:221], off
	v_lshl_add_u64 v[222:223], s[46:47], 0, v[130:131]
	s_mov_b32 m0, s77
	v_lshl_add_u64 v[224:225], s[52:53], 0, v[132:133]
	global_load_lds_dwordx4 v[222:223], off
	v_lshl_add_u64 v[222:223], s[46:47], 0, v[134:135]
	s_add_i32 m0, s77, 0x2000
	s_nop 0
	global_load_lds_dwordx4 v[222:223], off
	v_lshl_add_u64 v[222:223], s[52:53], 0, v[128:129]
	s_mov_b32 m0, s57
	s_nop 0
	global_load_lds_dwordx4 v[222:223], off
	s_mov_b32 m0, s58
	s_nop 0
	global_load_lds_dwordx4 v[224:225], off
	s_waitcnt vmcnt(8)
	s_waitcnt lgkmcnt(0)
	s_barrier
	s_setprio 1
	s_waitcnt lgkmcnt(0)
	v_mfma_f32_16x16x32_bf16 v[60:63], v[152:155], v[188:191], 0
	v_mfma_f32_16x16x32_bf16 v[60:63], v[156:159], v[192:195], v[60:63]
	v_mfma_f32_16x16x32_bf16 v[56:59], v[160:163], v[188:191], 0
	v_mfma_f32_16x16x32_bf16 v[56:59], v[164:167], v[192:195], v[56:59]
	v_mfma_f32_16x16x32_bf16 v[52:55], v[152:155], v[196:199], 0
	v_mfma_f32_16x16x32_bf16 v[52:55], v[156:159], v[200:203], v[52:55]
	v_mfma_f32_16x16x32_bf16 v[44:47], v[160:163], v[196:199], 0
	v_mfma_f32_16x16x32_bf16 v[44:47], v[164:167], v[200:203], v[44:47]
	v_mfma_f32_16x16x32_bf16 v[36:39], v[152:155], v[204:207], 0
	v_mfma_f32_16x16x32_bf16 v[36:39], v[156:159], v[208:211], v[36:39]
	v_mfma_f32_16x16x32_bf16 v[28:31], v[160:163], v[204:207], 0
	v_mfma_f32_16x16x32_bf16 v[28:31], v[164:167], v[208:211], v[28:31]
	v_mfma_f32_16x16x32_bf16 v[20:23], v[152:155], v[212:215], 0
	v_mfma_f32_16x16x32_bf16 v[20:23], v[156:159], v[216:219], v[20:23]
	v_mfma_f32_16x16x32_bf16 v[12:15], v[160:163], v[212:215], 0
	v_mfma_f32_16x16x32_bf16 v[12:15], v[164:167], v[216:219], v[12:15]
	v_mfma_f32_16x16x32_bf16 v[48:51], v[168:171], v[188:191], 0
	v_mfma_f32_16x16x32_bf16 v[48:51], v[172:175], v[192:195], v[48:51]
	v_mfma_f32_16x16x32_bf16 v[40:43], v[176:179], v[188:191], 0
	v_mfma_f32_16x16x32_bf16 v[40:43], v[184:187], v[192:195], v[40:43]
	v_mfma_f32_16x16x32_bf16 v[32:35], v[168:171], v[196:199], 0
	v_mfma_f32_16x16x32_bf16 v[32:35], v[172:175], v[200:203], v[32:35]
	v_mfma_f32_16x16x32_bf16 v[24:27], v[176:179], v[196:199], 0
	v_mfma_f32_16x16x32_bf16 v[24:27], v[184:187], v[200:203], v[24:27]
	v_mfma_f32_16x16x32_bf16 v[16:19], v[168:171], v[204:207], 0
	v_mfma_f32_16x16x32_bf16 v[16:19], v[172:175], v[208:211], v[16:19]
	v_mfma_f32_16x16x32_bf16 v[8:11], v[176:179], v[204:207], 0
	v_mfma_f32_16x16x32_bf16 v[8:11], v[184:187], v[208:211], v[8:11]
	v_mfma_f32_16x16x32_bf16 v[4:7], v[168:171], v[212:215], 0
	v_mfma_f32_16x16x32_bf16 v[4:7], v[172:175], v[216:219], v[4:7]
	v_mfma_f32_16x16x32_bf16 v[0:3], v[176:179], v[212:215], 0
	v_mfma_f32_16x16x32_bf16 v[0:3], v[184:187], v[216:219], v[0:3]
	s_setprio 0
	s_barrier
	s_branch .Lmid_gemm12
	.p2align	6
